# pads between consecutive LDS-DMA issue blocks widened from s_nop 0 to s_nop 3 (spacing the DMA issue), no setprio
# speedup vs baseline: 1.0066x; 1.0030x over previous
.Lnb_p1:
	s_add_i32 s7, s4, 0xfff84000
	s_cmp_eq_u32 s6, 28
	s_cselect_b32 s17, s0, s7
	s_cselect_b32 s16, s1, s5
	s_or_b32 s7, s17, 0x4000
	s_mov_b32 m0, s79
	s_nop 0
	buffer_load_dwordx4 v242, s[24:27], s4 offen lds
	s_nop 3
	s_mov_b32 m0, s83
	s_nop 0
	buffer_load_dwordx4 v243, s[24:27], s4 offen lds
	s_waitcnt vmcnt(24)
	s_waitcnt lgkmcnt(0)
	s_barrier
	s_waitcnt lgkmcnt(7)
	v_mfma_f32_16x16x32_bf16 v[180:183], v[16:19], v[192:195], 0
	v_mfma_f32_16x16x32_bf16 v[164:167], v[24:27], v[192:195], 0
	s_waitcnt lgkmcnt(5)
	v_mfma_f32_16x16x32_bf16 v[148:151], v[16:19], v[200:203], 0
	v_mfma_f32_16x16x32_bf16 v[140:143], v[24:27], v[200:203], 0
	s_waitcnt lgkmcnt(3)
	v_mfma_f32_16x16x32_bf16 v[132:135], v[16:19], v[220:223], 0
	v_mfma_f32_16x16x32_bf16 v[124:127], v[24:27], v[220:223], 0
	s_waitcnt lgkmcnt(1)
	v_mfma_f32_16x16x32_bf16 v[116:119], v[16:19], v[228:231], 0
	v_mfma_f32_16x16x32_bf16 v[108:111], v[24:27], v[228:231], 0
	v_mfma_f32_16x16x32_bf16 v[180:183], v[20:23], v[196:199], v[180:183]
	v_mfma_f32_16x16x32_bf16 v[164:167], v[28:31], v[196:199], v[164:167]
	v_mfma_f32_16x16x32_bf16 v[148:151], v[20:23], v[204:207], v[148:151]
	v_mfma_f32_16x16x32_bf16 v[140:143], v[28:31], v[204:207], v[140:143]
	v_mfma_f32_16x16x32_bf16 v[132:135], v[20:23], v[224:227], v[132:135]
	v_mfma_f32_16x16x32_bf16 v[124:127], v[28:31], v[224:227], v[124:127]
	s_waitcnt lgkmcnt(0)
	v_mfma_f32_16x16x32_bf16 v[116:119], v[20:23], v[246:249], v[116:119]
	v_mfma_f32_16x16x32_bf16 v[108:111], v[28:31], v[246:249], v[108:111]
	v_mfma_f32_16x16x32_bf16 v[172:175], v[152:155], v[192:195], 0
	v_mfma_f32_16x16x32_bf16 v[156:159], v[168:171], v[192:195], 0
	v_mfma_f32_16x16x32_bf16 v[144:147], v[152:155], v[200:203], 0
	v_mfma_f32_16x16x32_bf16 v[136:139], v[168:171], v[200:203], 0
	v_mfma_f32_16x16x32_bf16 v[128:131], v[152:155], v[220:223], 0
	v_mfma_f32_16x16x32_bf16 v[120:123], v[168:171], v[220:223], 0
	v_mfma_f32_16x16x32_bf16 v[112:115], v[152:155], v[228:231], 0
	v_mfma_f32_16x16x32_bf16 v[104:107], v[168:171], v[228:231], 0
	v_mfma_f32_16x16x32_bf16 v[172:175], v[160:163], v[196:199], v[172:175]
	v_mfma_f32_16x16x32_bf16 v[156:159], v[176:179], v[196:199], v[156:159]
	v_mfma_f32_16x16x32_bf16 v[144:147], v[160:163], v[204:207], v[144:147]
	v_mfma_f32_16x16x32_bf16 v[136:139], v[176:179], v[204:207], v[136:139]
	v_mfma_f32_16x16x32_bf16 v[128:131], v[160:163], v[224:227], v[128:131]
	v_mfma_f32_16x16x32_bf16 v[120:123], v[176:179], v[224:227], v[120:123]
	v_mfma_f32_16x16x32_bf16 v[112:115], v[160:163], v[246:249], v[112:115]
	v_mfma_f32_16x16x32_bf16 v[104:107], v[176:179], v[246:249], v[104:107]
	s_barrier
	ds_read_b128 v[192:195], v245 offset:16384
	ds_read_b128 v[196:199], v245 offset:17408
	ds_read_b128 v[200:203], v245 offset:18432
	ds_read_b128 v[204:207], v245 offset:19456
	ds_read_b128 v[220:223], v245 offset:20480
	ds_read_b128 v[224:227], v245 offset:21504
	ds_read_b128 v[228:231], v245 offset:22528
	ds_read_b128 v[246:249], v245 offset:23552
	s_mov_b32 m0, s51
	s_nop 0
	buffer_load_dwordx4 v242, s[56:59], s16 offen lds
	s_add_i32 s18, s16, 0x80000
	s_mov_b32 m0, s52
	s_nop 0
	buffer_load_dwordx4 v243, s[56:59], s16 offen lds
	s_nop 3
	s_mov_b32 m0, s53
	s_nop 0
	buffer_load_dwordx4 v242, s[56:59], s18 offen lds
	s_nop 3
	s_mov_b32 m0, s55
	s_nop 0
	buffer_load_dwordx4 v243, s[56:59], s18 offen lds
	s_nop 3
	s_mov_b32 m0, s31
	s_nop 0
	buffer_load_dwordx4 v242, s[24:27], s17 offen lds
	s_nop 3
	s_mov_b32 m0, s68
	s_nop 0
	buffer_load_dwordx4 v243, s[24:27], s17 offen lds
	s_waitcnt vmcnt(24)
	s_waitcnt lgkmcnt(0)
	s_barrier
	s_waitcnt lgkmcnt(7)
	v_mfma_f32_16x16x32_bf16 v[76:79], v[16:19], v[192:195], 0
	v_mfma_f32_16x16x32_bf16 v[68:71], v[24:27], v[192:195], 0
	s_waitcnt lgkmcnt(5)
	v_mfma_f32_16x16x32_bf16 v[60:63], v[16:19], v[200:203], 0
	v_mfma_f32_16x16x32_bf16 v[52:55], v[24:27], v[200:203], 0
	s_waitcnt lgkmcnt(3)
	v_mfma_f32_16x16x32_bf16 v[44:47], v[16:19], v[220:223], 0
	v_mfma_f32_16x16x32_bf16 v[36:39], v[24:27], v[220:223], 0
	s_waitcnt lgkmcnt(1)
	v_mfma_f32_16x16x32_bf16 v[12:15], v[16:19], v[228:231], 0
	v_mfma_f32_16x16x32_bf16 v[4:7], v[24:27], v[228:231], 0
	v_mfma_f32_16x16x32_bf16 v[76:79], v[20:23], v[196:199], v[76:79]
	v_mfma_f32_16x16x32_bf16 v[68:71], v[28:31], v[196:199], v[68:71]
	v_mfma_f32_16x16x32_bf16 v[60:63], v[20:23], v[204:207], v[60:63]
	v_mfma_f32_16x16x32_bf16 v[52:55], v[28:31], v[204:207], v[52:55]
	v_mfma_f32_16x16x32_bf16 v[44:47], v[20:23], v[224:227], v[44:47]
	v_mfma_f32_16x16x32_bf16 v[36:39], v[28:31], v[224:227], v[36:39]
	s_waitcnt lgkmcnt(0)
	v_mfma_f32_16x16x32_bf16 v[12:15], v[20:23], v[246:249], v[12:15]
	v_mfma_f32_16x16x32_bf16 v[4:7], v[28:31], v[246:249], v[4:7]
	v_mfma_f32_16x16x32_bf16 v[40:43], v[152:155], v[220:223], 0
	v_mfma_f32_16x16x32_bf16 v[32:35], v[168:171], v[220:223], 0
	v_mfma_f32_16x16x32_bf16 v[8:11], v[152:155], v[228:231], 0
	v_mfma_f32_16x16x32_bf16 v[0:3], v[168:171], v[228:231], 0
	v_mfma_f32_16x16x32_bf16 v[16:19], v[152:155], v[192:195], 0
	v_mfma_f32_16x16x32_bf16 v[20:23], v[168:171], v[192:195], 0
	v_mfma_f32_16x16x32_bf16 v[24:27], v[152:155], v[200:203], 0
	v_mfma_f32_16x16x32_bf16 v[28:31], v[168:171], v[200:203], 0
	v_mfma_f32_16x16x32_bf16 v[40:43], v[160:163], v[224:227], v[40:43]
	v_mfma_f32_16x16x32_bf16 v[32:35], v[176:179], v[224:227], v[32:35]
	v_mfma_f32_16x16x32_bf16 v[8:11], v[160:163], v[246:249], v[8:11]
	v_mfma_f32_16x16x32_bf16 v[0:3], v[176:179], v[246:249], v[0:3]
	v_mfma_f32_16x16x32_bf16 v[16:19], v[160:163], v[196:199], v[16:19]
	v_mfma_f32_16x16x32_bf16 v[20:23], v[176:179], v[196:199], v[20:23]
	v_mfma_f32_16x16x32_bf16 v[24:27], v[160:163], v[204:207], v[24:27]
	v_mfma_f32_16x16x32_bf16 v[28:31], v[176:179], v[204:207], v[28:31]
	s_barrier
	v_add_u32_e32 v72, 0x18000, v83
	v_add_u32_e32 v80, 0x1c000, v83
	ds_read_b128 v[48:51], v72
	ds_read_b128 v[56:59], v72 offset:1024
	ds_read_b128 v[64:67], v72 offset:2048
	ds_read_b128 v[72:75], v72 offset:3072
	ds_read_b128 v[152:155], v80
	ds_read_b128 v[160:163], v80 offset:1024
	ds_read_b128 v[168:171], v80 offset:2048
	ds_read_b128 v[176:179], v80 offset:3072
	ds_read_b128 v[192:195], v245 offset:32768
	ds_read_b128 v[196:199], v245 offset:33792
	ds_read_b128 v[200:203], v245 offset:34816
	ds_read_b128 v[204:207], v245 offset:35840
	ds_read_b128 v[220:223], v245 offset:36864
	ds_read_b128 v[224:227], v245 offset:37888
	ds_read_b128 v[228:231], v245 offset:38912
	ds_read_b128 v[246:249], v245 offset:39936
	s_add_i32 s17, s17, 0x80000
	s_mov_b32 m0, s69
	s_nop 0
	buffer_load_dwordx4 v242, s[24:27], s17 offen lds
	s_nop 3
	s_mov_b32 m0, s70
	s_nop 0
	buffer_load_dwordx4 v243, s[24:27], s17 offen lds
	s_waitcnt vmcnt(8)
	s_waitcnt lgkmcnt(0)
	s_barrier
	s_waitcnt lgkmcnt(7)
	v_mfma_f32_16x16x32_bf16 v[180:183], v[48:51], v[192:195], v[180:183]
	v_mfma_f32_16x16x32_bf16 v[164:167], v[64:67], v[192:195], v[164:167]
	s_waitcnt lgkmcnt(5)
	v_mfma_f32_16x16x32_bf16 v[148:151], v[48:51], v[200:203], v[148:151]
	v_mfma_f32_16x16x32_bf16 v[140:143], v[64:67], v[200:203], v[140:143]
	s_waitcnt lgkmcnt(3)
	v_mfma_f32_16x16x32_bf16 v[132:135], v[48:51], v[220:223], v[132:135]
	v_mfma_f32_16x16x32_bf16 v[124:127], v[64:67], v[220:223], v[124:127]
	s_waitcnt lgkmcnt(1)
	v_mfma_f32_16x16x32_bf16 v[116:119], v[48:51], v[228:231], v[116:119]
	v_mfma_f32_16x16x32_bf16 v[108:111], v[64:67], v[228:231], v[108:111]
	v_mfma_f32_16x16x32_bf16 v[180:183], v[56:59], v[196:199], v[180:183]
	v_mfma_f32_16x16x32_bf16 v[164:167], v[72:75], v[196:199], v[164:167]
	v_mfma_f32_16x16x32_bf16 v[148:151], v[56:59], v[204:207], v[148:151]
	v_mfma_f32_16x16x32_bf16 v[140:143], v[72:75], v[204:207], v[140:143]
	v_mfma_f32_16x16x32_bf16 v[132:135], v[56:59], v[224:227], v[132:135]
	v_mfma_f32_16x16x32_bf16 v[124:127], v[72:75], v[224:227], v[124:127]
	s_waitcnt lgkmcnt(0)
	v_mfma_f32_16x16x32_bf16 v[116:119], v[56:59], v[246:249], v[116:119]
	v_mfma_f32_16x16x32_bf16 v[108:111], v[72:75], v[246:249], v[108:111]
	v_mfma_f32_16x16x32_bf16 v[172:175], v[152:155], v[192:195], v[172:175]
	v_mfma_f32_16x16x32_bf16 v[156:159], v[168:171], v[192:195], v[156:159]
	v_mfma_f32_16x16x32_bf16 v[144:147], v[152:155], v[200:203], v[144:147]
	v_mfma_f32_16x16x32_bf16 v[136:139], v[168:171], v[200:203], v[136:139]
	v_mfma_f32_16x16x32_bf16 v[128:131], v[152:155], v[220:223], v[128:131]
	v_mfma_f32_16x16x32_bf16 v[120:123], v[168:171], v[220:223], v[120:123]
	v_mfma_f32_16x16x32_bf16 v[112:115], v[152:155], v[228:231], v[112:115]
	v_mfma_f32_16x16x32_bf16 v[104:107], v[168:171], v[228:231], v[104:107]
	v_mfma_f32_16x16x32_bf16 v[172:175], v[160:163], v[196:199], v[172:175]
	v_mfma_f32_16x16x32_bf16 v[156:159], v[176:179], v[196:199], v[156:159]
	v_mfma_f32_16x16x32_bf16 v[144:147], v[160:163], v[204:207], v[144:147]
	v_mfma_f32_16x16x32_bf16 v[136:139], v[176:179], v[204:207], v[136:139]
	v_mfma_f32_16x16x32_bf16 v[128:131], v[160:163], v[224:227], v[128:131]
	v_mfma_f32_16x16x32_bf16 v[120:123], v[176:179], v[224:227], v[120:123]
	v_mfma_f32_16x16x32_bf16 v[112:115], v[160:163], v[246:249], v[112:115]
	v_mfma_f32_16x16x32_bf16 v[104:107], v[176:179], v[246:249], v[104:107]
	s_barrier
	ds_read_b128 v[192:195], v245 offset:49152
	ds_read_b128 v[196:199], v245 offset:50176
	ds_read_b128 v[200:203], v245 offset:51200
	ds_read_b128 v[204:207], v245 offset:52224
	ds_read_b128 v[220:223], v245 offset:53248
	ds_read_b128 v[224:227], v245 offset:54272
	ds_read_b128 v[228:231], v245 offset:55296
	ds_read_b128 v[246:249], v245 offset:56320
	s_or_b32 s17, s16, 0x4000
	s_mov_b32 m0, s73
	s_nop 0
	buffer_load_dwordx4 v242, s[56:59], s17 offen lds
	s_add_i32 s16, s16, 0x84000
	s_mov_b32 m0, s74
	s_nop 0
	buffer_load_dwordx4 v243, s[56:59], s17 offen lds
	s_nop 3
	s_mov_b32 m0, s77
	s_nop 0
	buffer_load_dwordx4 v242, s[56:59], s16 offen lds
	s_nop 3
	s_mov_b32 m0, s78
	s_nop 0
	buffer_load_dwordx4 v243, s[56:59], s16 offen lds
	s_nop 3
	s_mov_b32 m0, s75
	s_nop 0
	buffer_load_dwordx4 v242, s[24:27], s7 offen lds
	s_nop 3
	s_mov_b32 m0, s76
	s_nop 0
	buffer_load_dwordx4 v243, s[24:27], s7 offen lds
	s_waitcnt vmcnt(8)
	s_waitcnt lgkmcnt(0)
	s_barrier
	s_waitcnt lgkmcnt(7)
	v_mfma_f32_16x16x32_bf16 v[76:79], v[48:51], v[192:195], v[76:79]
	v_mfma_f32_16x16x32_bf16 v[68:71], v[64:67], v[192:195], v[68:71]
	s_waitcnt lgkmcnt(5)
	v_mfma_f32_16x16x32_bf16 v[60:63], v[48:51], v[200:203], v[60:63]
	v_mfma_f32_16x16x32_bf16 v[52:55], v[64:67], v[200:203], v[52:55]
	s_waitcnt lgkmcnt(3)
	v_mfma_f32_16x16x32_bf16 v[44:47], v[48:51], v[220:223], v[44:47]
	v_mfma_f32_16x16x32_bf16 v[36:39], v[64:67], v[220:223], v[36:39]
	s_waitcnt lgkmcnt(1)
	v_mfma_f32_16x16x32_bf16 v[12:15], v[48:51], v[228:231], v[12:15]
	v_mfma_f32_16x16x32_bf16 v[4:7], v[64:67], v[228:231], v[4:7]
	v_mfma_f32_16x16x32_bf16 v[76:79], v[56:59], v[196:199], v[76:79]
	v_mfma_f32_16x16x32_bf16 v[68:71], v[72:75], v[196:199], v[68:71]
	v_mfma_f32_16x16x32_bf16 v[60:63], v[56:59], v[204:207], v[60:63]
	v_mfma_f32_16x16x32_bf16 v[52:55], v[72:75], v[204:207], v[52:55]
	v_mfma_f32_16x16x32_bf16 v[44:47], v[56:59], v[224:227], v[44:47]
	v_mfma_f32_16x16x32_bf16 v[36:39], v[72:75], v[224:227], v[36:39]
	s_waitcnt lgkmcnt(0)
	v_mfma_f32_16x16x32_bf16 v[12:15], v[56:59], v[246:249], v[12:15]
	v_mfma_f32_16x16x32_bf16 v[4:7], v[72:75], v[246:249], v[4:7]
	v_mfma_f32_16x16x32_bf16 v[16:19], v[152:155], v[192:195], v[16:19]
	v_mfma_f32_16x16x32_bf16 v[72:75], v[160:163], v[196:199], v[16:19]
	v_mfma_f32_16x16x32_bf16 v[16:19], v[168:171], v[192:195], v[20:23]
	v_mfma_f32_16x16x32_bf16 v[64:67], v[176:179], v[196:199], v[16:19]
	v_mfma_f32_16x16x32_bf16 v[16:19], v[152:155], v[200:203], v[24:27]
	v_mfma_f32_16x16x32_bf16 v[56:59], v[160:163], v[204:207], v[16:19]
	v_mfma_f32_16x16x32_bf16 v[16:19], v[168:171], v[200:203], v[28:31]
	v_mfma_f32_16x16x32_bf16 v[48:51], v[176:179], v[204:207], v[16:19]
	v_mfma_f32_16x16x32_bf16 v[16:19], v[152:155], v[220:223], v[40:43]
	v_mfma_f32_16x16x32_bf16 v[40:43], v[160:163], v[224:227], v[16:19]
	v_mfma_f32_16x16x32_bf16 v[16:19], v[168:171], v[220:223], v[32:35]
	v_mfma_f32_16x16x32_bf16 v[8:11], v[152:155], v[228:231], v[8:11]
	v_mfma_f32_16x16x32_bf16 v[0:3], v[168:171], v[228:231], v[0:3]
	v_mfma_f32_16x16x32_bf16 v[32:35], v[176:179], v[224:227], v[16:19]
	v_mfma_f32_16x16x32_bf16 v[8:11], v[160:163], v[246:249], v[8:11]
	v_mfma_f32_16x16x32_bf16 v[0:3], v[176:179], v[246:249], v[0:3]
	s_barrier
	s_add_i32 s6, s6, 2
	s_add_i32 s4, s4, 0x8000
	s_add_i32 s5, s5, 0x8000
.LBB0_143:
	v_add_u32_e32 v28, 0x10000, v83
	v_add_u32_e32 v80, 0x14000, v83
	ds_read_b128 v[16:19], v28
	ds_read_b128 v[20:23], v28 offset:1024
	ds_read_b128 v[24:27], v28 offset:2048
	ds_read_b128 v[28:31], v28 offset:3072
	ds_read_b128 v[152:155], v80
	ds_read_b128 v[160:163], v80 offset:1024
	ds_read_b128 v[168:171], v80 offset:2048
	ds_read_b128 v[176:179], v80 offset:3072
	s_add_i32 s7, s4, 0xfff84000
	s_cmp_eq_u32 s6, 28
	s_cselect_b32 s17, s0, s7
	s_cselect_b32 s16, s1, s5
	s_or_b32 s7, s17, 0x4000
	ds_read_b128 v[192:195], v245
	ds_read_b128 v[196:199], v245 offset:1024
	ds_read_b128 v[200:203], v245 offset:2048
	ds_read_b128 v[204:207], v245 offset:3072
	ds_read_b128 v[220:223], v245 offset:4096
	ds_read_b128 v[224:227], v245 offset:5120
	ds_read_b128 v[228:231], v245 offset:6144
	ds_read_b128 v[246:249], v245 offset:7168
	s_mov_b32 m0, s79
	s_nop 0
	buffer_load_dwordx4 v242, s[24:27], s4 offen lds
	s_nop 3
	s_mov_b32 m0, s83
	s_nop 0
	buffer_load_dwordx4 v243, s[24:27], s4 offen lds
	s_waitcnt vmcnt(8)
	s_waitcnt lgkmcnt(0)
	s_barrier
	s_waitcnt lgkmcnt(7)
	v_mfma_f32_16x16x32_bf16 v[180:183], v[16:19], v[192:195], v[180:183]
	v_mfma_f32_16x16x32_bf16 v[164:167], v[24:27], v[192:195], v[164:167]
	s_waitcnt lgkmcnt(5)
	v_mfma_f32_16x16x32_bf16 v[148:151], v[16:19], v[200:203], v[148:151]
	v_mfma_f32_16x16x32_bf16 v[140:143], v[24:27], v[200:203], v[140:143]
	s_waitcnt lgkmcnt(3)
	v_mfma_f32_16x16x32_bf16 v[132:135], v[16:19], v[220:223], v[132:135]
	v_mfma_f32_16x16x32_bf16 v[124:127], v[24:27], v[220:223], v[124:127]
	s_waitcnt lgkmcnt(1)
	v_mfma_f32_16x16x32_bf16 v[116:119], v[16:19], v[228:231], v[116:119]
	v_mfma_f32_16x16x32_bf16 v[108:111], v[24:27], v[228:231], v[108:111]
	v_mfma_f32_16x16x32_bf16 v[180:183], v[20:23], v[196:199], v[180:183]
	v_mfma_f32_16x16x32_bf16 v[164:167], v[28:31], v[196:199], v[164:167]
	v_mfma_f32_16x16x32_bf16 v[148:151], v[20:23], v[204:207], v[148:151]
	v_mfma_f32_16x16x32_bf16 v[140:143], v[28:31], v[204:207], v[140:143]
	v_mfma_f32_16x16x32_bf16 v[132:135], v[20:23], v[224:227], v[132:135]
	v_mfma_f32_16x16x32_bf16 v[124:127], v[28:31], v[224:227], v[124:127]
	s_waitcnt lgkmcnt(0)
	v_mfma_f32_16x16x32_bf16 v[116:119], v[20:23], v[246:249], v[116:119]
	v_mfma_f32_16x16x32_bf16 v[108:111], v[28:31], v[246:249], v[108:111]
	v_mfma_f32_16x16x32_bf16 v[172:175], v[152:155], v[192:195], v[172:175]
	v_mfma_f32_16x16x32_bf16 v[156:159], v[168:171], v[192:195], v[156:159]
	v_mfma_f32_16x16x32_bf16 v[144:147], v[152:155], v[200:203], v[144:147]
	v_mfma_f32_16x16x32_bf16 v[136:139], v[168:171], v[200:203], v[136:139]
	v_mfma_f32_16x16x32_bf16 v[128:131], v[152:155], v[220:223], v[128:131]
	v_mfma_f32_16x16x32_bf16 v[120:123], v[168:171], v[220:223], v[120:123]
	v_mfma_f32_16x16x32_bf16 v[112:115], v[152:155], v[228:231], v[112:115]
	v_mfma_f32_16x16x32_bf16 v[104:107], v[168:171], v[228:231], v[104:107]
	v_mfma_f32_16x16x32_bf16 v[172:175], v[160:163], v[196:199], v[172:175]
	v_mfma_f32_16x16x32_bf16 v[156:159], v[176:179], v[196:199], v[156:159]
	v_mfma_f32_16x16x32_bf16 v[144:147], v[160:163], v[204:207], v[144:147]
	v_mfma_f32_16x16x32_bf16 v[136:139], v[176:179], v[204:207], v[136:139]
	v_mfma_f32_16x16x32_bf16 v[128:131], v[160:163], v[224:227], v[128:131]
	v_mfma_f32_16x16x32_bf16 v[120:123], v[176:179], v[224:227], v[120:123]
	v_mfma_f32_16x16x32_bf16 v[112:115], v[160:163], v[246:249], v[112:115]
	v_mfma_f32_16x16x32_bf16 v[104:107], v[176:179], v[246:249], v[104:107]
	s_barrier
	ds_read_b128 v[192:195], v245 offset:16384
	ds_read_b128 v[196:199], v245 offset:17408
	ds_read_b128 v[200:203], v245 offset:18432
	ds_read_b128 v[204:207], v245 offset:19456
	ds_read_b128 v[220:223], v245 offset:20480
	ds_read_b128 v[224:227], v245 offset:21504
	ds_read_b128 v[228:231], v245 offset:22528
	ds_read_b128 v[246:249], v245 offset:23552
	s_mov_b32 m0, s51
	s_nop 0
	buffer_load_dwordx4 v242, s[56:59], s16 offen lds
	s_add_i32 s18, s16, 0x80000
	s_mov_b32 m0, s52
	s_nop 0
	buffer_load_dwordx4 v243, s[56:59], s16 offen lds
	s_nop 3
	s_mov_b32 m0, s53
	s_nop 0
	buffer_load_dwordx4 v242, s[56:59], s18 offen lds
	s_nop 3
	s_mov_b32 m0, s55
	s_nop 0
	buffer_load_dwordx4 v243, s[56:59], s18 offen lds
	s_nop 3
	s_mov_b32 m0, s31
	s_nop 0
	buffer_load_dwordx4 v242, s[24:27], s17 offen lds
	s_nop 3
	s_mov_b32 m0, s68
	s_nop 0
	buffer_load_dwordx4 v243, s[24:27], s17 offen lds
	s_waitcnt vmcnt(8)
	s_waitcnt lgkmcnt(0)
	s_barrier
	s_waitcnt lgkmcnt(7)
	v_mfma_f32_16x16x32_bf16 v[76:79], v[16:19], v[192:195], v[76:79]
	v_mfma_f32_16x16x32_bf16 v[68:71], v[24:27], v[192:195], v[68:71]
	s_waitcnt lgkmcnt(5)
	v_mfma_f32_16x16x32_bf16 v[60:63], v[16:19], v[200:203], v[60:63]
	v_mfma_f32_16x16x32_bf16 v[52:55], v[24:27], v[200:203], v[52:55]
	s_waitcnt lgkmcnt(3)
	v_mfma_f32_16x16x32_bf16 v[44:47], v[16:19], v[220:223], v[44:47]
	v_mfma_f32_16x16x32_bf16 v[36:39], v[24:27], v[220:223], v[36:39]
	s_waitcnt lgkmcnt(1)
	v_mfma_f32_16x16x32_bf16 v[12:15], v[16:19], v[228:231], v[12:15]
	v_mfma_f32_16x16x32_bf16 v[4:7], v[24:27], v[228:231], v[4:7]
	v_mfma_f32_16x16x32_bf16 v[76:79], v[20:23], v[196:199], v[76:79]
	v_mfma_f32_16x16x32_bf16 v[68:71], v[28:31], v[196:199], v[68:71]
	v_mfma_f32_16x16x32_bf16 v[60:63], v[20:23], v[204:207], v[60:63]
	v_mfma_f32_16x16x32_bf16 v[52:55], v[28:31], v[204:207], v[52:55]
	v_mfma_f32_16x16x32_bf16 v[44:47], v[20:23], v[224:227], v[44:47]
	v_mfma_f32_16x16x32_bf16 v[36:39], v[28:31], v[224:227], v[36:39]
	s_waitcnt lgkmcnt(0)
	v_mfma_f32_16x16x32_bf16 v[12:15], v[20:23], v[246:249], v[12:15]
	v_mfma_f32_16x16x32_bf16 v[4:7], v[28:31], v[246:249], v[4:7]
	v_mfma_f32_16x16x32_bf16 v[40:43], v[152:155], v[220:223], v[40:43]
	v_mfma_f32_16x16x32_bf16 v[32:35], v[168:171], v[220:223], v[32:35]
	v_mfma_f32_16x16x32_bf16 v[8:11], v[152:155], v[228:231], v[8:11]
	v_mfma_f32_16x16x32_bf16 v[0:3], v[168:171], v[228:231], v[0:3]
	v_mfma_f32_16x16x32_bf16 v[16:19], v[152:155], v[192:195], v[72:75]
	v_mfma_f32_16x16x32_bf16 v[20:23], v[168:171], v[192:195], v[64:67]
	v_mfma_f32_16x16x32_bf16 v[24:27], v[152:155], v[200:203], v[56:59]
	v_mfma_f32_16x16x32_bf16 v[28:31], v[168:171], v[200:203], v[48:51]
	v_mfma_f32_16x16x32_bf16 v[40:43], v[160:163], v[224:227], v[40:43]
	v_mfma_f32_16x16x32_bf16 v[32:35], v[176:179], v[224:227], v[32:35]
	v_mfma_f32_16x16x32_bf16 v[8:11], v[160:163], v[246:249], v[8:11]
	v_mfma_f32_16x16x32_bf16 v[0:3], v[176:179], v[246:249], v[0:3]
	v_mfma_f32_16x16x32_bf16 v[16:19], v[160:163], v[196:199], v[16:19]
	v_mfma_f32_16x16x32_bf16 v[20:23], v[176:179], v[196:199], v[20:23]
	v_mfma_f32_16x16x32_bf16 v[24:27], v[160:163], v[204:207], v[24:27]
	v_mfma_f32_16x16x32_bf16 v[28:31], v[176:179], v[204:207], v[28:31]
	s_barrier
	v_add_u32_e32 v72, 0x18000, v83
	v_add_u32_e32 v80, 0x1c000, v83
	ds_read_b128 v[48:51], v72
	ds_read_b128 v[56:59], v72 offset:1024
	ds_read_b128 v[64:67], v72 offset:2048
	ds_read_b128 v[72:75], v72 offset:3072
	ds_read_b128 v[152:155], v80
	ds_read_b128 v[160:163], v80 offset:1024
	ds_read_b128 v[168:171], v80 offset:2048
	ds_read_b128 v[176:179], v80 offset:3072
	ds_read_b128 v[192:195], v245 offset:32768
	ds_read_b128 v[196:199], v245 offset:33792
	ds_read_b128 v[200:203], v245 offset:34816
	ds_read_b128 v[204:207], v245 offset:35840
	ds_read_b128 v[220:223], v245 offset:36864
	ds_read_b128 v[224:227], v245 offset:37888
	ds_read_b128 v[228:231], v245 offset:38912
	ds_read_b128 v[246:249], v245 offset:39936
	s_add_i32 s17, s17, 0x80000
	s_mov_b32 m0, s69
	s_nop 0
	buffer_load_dwordx4 v242, s[24:27], s17 offen lds
	s_nop 3
	s_mov_b32 m0, s70
	s_nop 0
	buffer_load_dwordx4 v243, s[24:27], s17 offen lds
	s_waitcnt vmcnt(8)
	s_waitcnt lgkmcnt(0)
	s_barrier
	s_waitcnt lgkmcnt(7)
	v_mfma_f32_16x16x32_bf16 v[180:183], v[48:51], v[192:195], v[180:183]
	v_mfma_f32_16x16x32_bf16 v[164:167], v[64:67], v[192:195], v[164:167]
	s_waitcnt lgkmcnt(5)
	v_mfma_f32_16x16x32_bf16 v[148:151], v[48:51], v[200:203], v[148:151]
	v_mfma_f32_16x16x32_bf16 v[140:143], v[64:67], v[200:203], v[140:143]
	s_waitcnt lgkmcnt(3)
	v_mfma_f32_16x16x32_bf16 v[132:135], v[48:51], v[220:223], v[132:135]
	v_mfma_f32_16x16x32_bf16 v[124:127], v[64:67], v[220:223], v[124:127]
	s_waitcnt lgkmcnt(1)
	v_mfma_f32_16x16x32_bf16 v[116:119], v[48:51], v[228:231], v[116:119]
	v_mfma_f32_16x16x32_bf16 v[108:111], v[64:67], v[228:231], v[108:111]
	v_mfma_f32_16x16x32_bf16 v[180:183], v[56:59], v[196:199], v[180:183]
	v_mfma_f32_16x16x32_bf16 v[164:167], v[72:75], v[196:199], v[164:167]
	v_mfma_f32_16x16x32_bf16 v[148:151], v[56:59], v[204:207], v[148:151]
	v_mfma_f32_16x16x32_bf16 v[140:143], v[72:75], v[204:207], v[140:143]
	v_mfma_f32_16x16x32_bf16 v[132:135], v[56:59], v[224:227], v[132:135]
	v_mfma_f32_16x16x32_bf16 v[124:127], v[72:75], v[224:227], v[124:127]
	s_waitcnt lgkmcnt(0)
	v_mfma_f32_16x16x32_bf16 v[116:119], v[56:59], v[246:249], v[116:119]
	v_mfma_f32_16x16x32_bf16 v[108:111], v[72:75], v[246:249], v[108:111]
	v_mfma_f32_16x16x32_bf16 v[172:175], v[152:155], v[192:195], v[172:175]
	v_mfma_f32_16x16x32_bf16 v[156:159], v[168:171], v[192:195], v[156:159]
	v_mfma_f32_16x16x32_bf16 v[144:147], v[152:155], v[200:203], v[144:147]
	v_mfma_f32_16x16x32_bf16 v[136:139], v[168:171], v[200:203], v[136:139]
	v_mfma_f32_16x16x32_bf16 v[128:131], v[152:155], v[220:223], v[128:131]
	v_mfma_f32_16x16x32_bf16 v[120:123], v[168:171], v[220:223], v[120:123]
	v_mfma_f32_16x16x32_bf16 v[112:115], v[152:155], v[228:231], v[112:115]
	v_mfma_f32_16x16x32_bf16 v[104:107], v[168:171], v[228:231], v[104:107]
	v_mfma_f32_16x16x32_bf16 v[172:175], v[160:163], v[196:199], v[172:175]
	v_mfma_f32_16x16x32_bf16 v[156:159], v[176:179], v[196:199], v[156:159]
	v_mfma_f32_16x16x32_bf16 v[144:147], v[160:163], v[204:207], v[144:147]
	v_mfma_f32_16x16x32_bf16 v[136:139], v[176:179], v[204:207], v[136:139]
	v_mfma_f32_16x16x32_bf16 v[128:131], v[160:163], v[224:227], v[128:131]
	v_mfma_f32_16x16x32_bf16 v[120:123], v[176:179], v[224:227], v[120:123]
	v_mfma_f32_16x16x32_bf16 v[112:115], v[160:163], v[246:249], v[112:115]
	v_mfma_f32_16x16x32_bf16 v[104:107], v[176:179], v[246:249], v[104:107]
	s_barrier
	ds_read_b128 v[192:195], v245 offset:49152
	ds_read_b128 v[196:199], v245 offset:50176
	ds_read_b128 v[200:203], v245 offset:51200
	ds_read_b128 v[204:207], v245 offset:52224
	ds_read_b128 v[220:223], v245 offset:53248
	ds_read_b128 v[224:227], v245 offset:54272
	ds_read_b128 v[228:231], v245 offset:55296
	ds_read_b128 v[246:249], v245 offset:56320
	s_or_b32 s17, s16, 0x4000
	s_mov_b32 m0, s73
	s_nop 0
	buffer_load_dwordx4 v242, s[56:59], s17 offen lds
	s_add_i32 s16, s16, 0x84000
	s_mov_b32 m0, s74
	s_nop 0
	buffer_load_dwordx4 v243, s[56:59], s17 offen lds
	s_nop 3
	s_mov_b32 m0, s77
	s_nop 0
	buffer_load_dwordx4 v242, s[56:59], s16 offen lds
	s_nop 3
	s_mov_b32 m0, s78
	s_nop 0
	buffer_load_dwordx4 v243, s[56:59], s16 offen lds
	s_nop 3
	s_mov_b32 m0, s75
	s_nop 0
	buffer_load_dwordx4 v242, s[24:27], s7 offen lds
	s_nop 3
	s_mov_b32 m0, s76
	s_nop 0
	buffer_load_dwordx4 v243, s[24:27], s7 offen lds
	s_waitcnt vmcnt(8)
	s_waitcnt lgkmcnt(0)
	s_barrier
	s_waitcnt lgkmcnt(7)
	v_mfma_f32_16x16x32_bf16 v[76:79], v[48:51], v[192:195], v[76:79]
	v_mfma_f32_16x16x32_bf16 v[68:71], v[64:67], v[192:195], v[68:71]
	s_waitcnt lgkmcnt(5)
	v_mfma_f32_16x16x32_bf16 v[60:63], v[48:51], v[200:203], v[60:63]
	v_mfma_f32_16x16x32_bf16 v[52:55], v[64:67], v[200:203], v[52:55]
	s_waitcnt lgkmcnt(3)
	v_mfma_f32_16x16x32_bf16 v[44:47], v[48:51], v[220:223], v[44:47]
	v_mfma_f32_16x16x32_bf16 v[36:39], v[64:67], v[220:223], v[36:39]
	s_waitcnt lgkmcnt(1)
	v_mfma_f32_16x16x32_bf16 v[12:15], v[48:51], v[228:231], v[12:15]
	v_mfma_f32_16x16x32_bf16 v[4:7], v[64:67], v[228:231], v[4:7]
	v_mfma_f32_16x16x32_bf16 v[76:79], v[56:59], v[196:199], v[76:79]
	v_mfma_f32_16x16x32_bf16 v[68:71], v[72:75], v[196:199], v[68:71]
	v_mfma_f32_16x16x32_bf16 v[60:63], v[56:59], v[204:207], v[60:63]
	v_mfma_f32_16x16x32_bf16 v[52:55], v[72:75], v[204:207], v[52:55]
	v_mfma_f32_16x16x32_bf16 v[44:47], v[56:59], v[224:227], v[44:47]
	v_mfma_f32_16x16x32_bf16 v[36:39], v[72:75], v[224:227], v[36:39]
	s_waitcnt lgkmcnt(0)
	v_mfma_f32_16x16x32_bf16 v[12:15], v[56:59], v[246:249], v[12:15]
	v_mfma_f32_16x16x32_bf16 v[4:7], v[72:75], v[246:249], v[4:7]
	v_mfma_f32_16x16x32_bf16 v[16:19], v[152:155], v[192:195], v[16:19]
	v_mfma_f32_16x16x32_bf16 v[72:75], v[160:163], v[196:199], v[16:19]
	v_mfma_f32_16x16x32_bf16 v[16:19], v[168:171], v[192:195], v[20:23]
	v_mfma_f32_16x16x32_bf16 v[64:67], v[176:179], v[196:199], v[16:19]
	v_mfma_f32_16x16x32_bf16 v[16:19], v[152:155], v[200:203], v[24:27]
	v_mfma_f32_16x16x32_bf16 v[56:59], v[160:163], v[204:207], v[16:19]
	v_mfma_f32_16x16x32_bf16 v[16:19], v[168:171], v[200:203], v[28:31]
	v_mfma_f32_16x16x32_bf16 v[48:51], v[176:179], v[204:207], v[16:19]
	v_mfma_f32_16x16x32_bf16 v[16:19], v[152:155], v[220:223], v[40:43]
	v_mfma_f32_16x16x32_bf16 v[40:43], v[160:163], v[224:227], v[16:19]
	v_mfma_f32_16x16x32_bf16 v[16:19], v[168:171], v[220:223], v[32:35]
	v_mfma_f32_16x16x32_bf16 v[8:11], v[152:155], v[228:231], v[8:11]
	v_mfma_f32_16x16x32_bf16 v[0:3], v[168:171], v[228:231], v[0:3]
	v_mfma_f32_16x16x32_bf16 v[32:35], v[176:179], v[224:227], v[16:19]
	v_mfma_f32_16x16x32_bf16 v[8:11], v[160:163], v[246:249], v[8:11]
	v_mfma_f32_16x16x32_bf16 v[0:3], v[176:179], v[246:249], v[0:3]
	s_barrier
	s_add_i32 s6, s6, 2
	s_add_i32 s4, s4, 0x8000
	s_add_i32 s5, s5, 0x8000
	s_cmp_gt_u32 s6, 29
	s_cbranch_scc0 .LBB0_143

.LBB0_594:
	v_add_u32_e32 v80, 0x10000, v226
	ds_read_b128 v[152:155], v80
	ds_read_b128 v[156:159], v80 offset:1024
	ds_read_b128 v[160:163], v80 offset:2048
	ds_read_b128 v[164:167], v80 offset:3072
	v_add_u32_e32 v80, 0x14000, v226
	ds_read_b128 v[168:171], v80
	ds_read_b128 v[172:175], v80 offset:1024
	ds_read_b128 v[176:179], v80 offset:2048
	ds_read_b128 v[180:183], v80 offset:3072
	s_add_i32 s97, s96, s39
	s_add_i32 s94, s97, 0x8000
	s_add_i32 s95, s93, s39
	s_cmp_eq_u32 s39, 0x78000
	s_cselect_b32 s36, vcc_lo, s94
	s_cselect_b32 s95, vcc_hi, s95
	s_or_b32 s94, s36, 0x4000
	ds_read_b128 v[184:187], v227
	ds_read_b128 v[188:191], v227 offset:1024
	ds_read_b128 v[192:195], v227 offset:2048
	ds_read_b128 v[196:199], v227 offset:3072
	ds_read_b128 v[200:203], v227 offset:4096
	ds_read_b128 v[204:207], v227 offset:5120
	ds_read_b128 v[228:231], v227 offset:6144
	ds_read_b128 v[240:243], v227 offset:7168
	s_add_i32 s97, s97, 0x84000
	s_mov_b32 m0, s85
	s_nop 0
	buffer_load_dwordx4 v224, s[60:63], s97 offen lds
	s_nop 3
	s_mov_b32 m0, s86
	s_nop 0
	buffer_load_dwordx4 v225, s[60:63], s97 offen lds
	s_waitcnt vmcnt(8)
	s_waitcnt lgkmcnt(0)
	s_barrier
	s_waitcnt lgkmcnt(7)
	v_mfma_f32_16x16x32_bf16 v[148:151], v[152:155], v[184:187], v[148:151]
	v_mfma_f32_16x16x32_bf16 v[144:147], v[160:163], v[184:187], v[144:147]
	s_waitcnt lgkmcnt(5)
	v_mfma_f32_16x16x32_bf16 v[132:135], v[152:155], v[192:195], v[132:135]
	v_mfma_f32_16x16x32_bf16 v[128:131], v[160:163], v[192:195], v[128:131]
	s_waitcnt lgkmcnt(3)
	v_mfma_f32_16x16x32_bf16 v[116:119], v[152:155], v[200:203], v[116:119]
	v_mfma_f32_16x16x32_bf16 v[112:115], v[160:163], v[200:203], v[112:115]
	s_waitcnt lgkmcnt(1)
	v_mfma_f32_16x16x32_bf16 v[76:79], v[152:155], v[228:231], v[76:79]
	v_mfma_f32_16x16x32_bf16 v[72:75], v[160:163], v[228:231], v[72:75]
	v_mfma_f32_16x16x32_bf16 v[148:151], v[156:159], v[188:191], v[148:151]
	v_mfma_f32_16x16x32_bf16 v[144:147], v[164:167], v[188:191], v[144:147]
	v_mfma_f32_16x16x32_bf16 v[132:135], v[156:159], v[196:199], v[132:135]
	v_mfma_f32_16x16x32_bf16 v[128:131], v[164:167], v[196:199], v[128:131]
	v_mfma_f32_16x16x32_bf16 v[116:119], v[156:159], v[204:207], v[116:119]
	v_mfma_f32_16x16x32_bf16 v[112:115], v[164:167], v[204:207], v[112:115]
	s_waitcnt lgkmcnt(0)
	v_mfma_f32_16x16x32_bf16 v[76:79], v[156:159], v[240:243], v[76:79]
	v_mfma_f32_16x16x32_bf16 v[72:75], v[164:167], v[240:243], v[72:75]
	v_mfma_f32_16x16x32_bf16 v[140:143], v[168:171], v[184:187], v[140:143]
	v_mfma_f32_16x16x32_bf16 v[136:139], v[176:179], v[184:187], v[136:139]
	v_mfma_f32_16x16x32_bf16 v[124:127], v[168:171], v[192:195], v[124:127]
	v_mfma_f32_16x16x32_bf16 v[120:123], v[176:179], v[192:195], v[120:123]
	v_mfma_f32_16x16x32_bf16 v[108:111], v[168:171], v[200:203], v[108:111]
	v_mfma_f32_16x16x32_bf16 v[104:107], v[176:179], v[200:203], v[104:107]
	v_mfma_f32_16x16x32_bf16 v[68:71], v[168:171], v[228:231], v[68:71]
	v_mfma_f32_16x16x32_bf16 v[64:67], v[176:179], v[228:231], v[64:67]
	v_mfma_f32_16x16x32_bf16 v[140:143], v[172:175], v[188:191], v[140:143]
	v_mfma_f32_16x16x32_bf16 v[136:139], v[180:183], v[188:191], v[136:139]
	v_mfma_f32_16x16x32_bf16 v[124:127], v[172:175], v[196:199], v[124:127]
	v_mfma_f32_16x16x32_bf16 v[120:123], v[180:183], v[196:199], v[120:123]
	v_mfma_f32_16x16x32_bf16 v[108:111], v[172:175], v[204:207], v[108:111]
	v_mfma_f32_16x16x32_bf16 v[104:107], v[180:183], v[204:207], v[104:107]
	v_mfma_f32_16x16x32_bf16 v[68:71], v[172:175], v[240:243], v[68:71]
	v_mfma_f32_16x16x32_bf16 v[64:67], v[180:183], v[240:243], v[64:67]
	s_barrier
	ds_read_b128 v[184:187], v227 offset:16384
	ds_read_b128 v[188:191], v227 offset:17408
	ds_read_b128 v[192:195], v227 offset:18432
	ds_read_b128 v[196:199], v227 offset:19456
	ds_read_b128 v[200:203], v227 offset:20480
	ds_read_b128 v[204:207], v227 offset:21504
	ds_read_b128 v[228:231], v227 offset:22528
	ds_read_b128 v[240:243], v227 offset:23552
	s_mov_b32 m0, s34
	s_nop 0
	buffer_load_dwordx4 v224, s[48:51], s95 offen lds
	s_add_i32 s97, s95, 0x80000
	s_mov_b32 m0, s55
	s_nop 0
	buffer_load_dwordx4 v225, s[48:51], s95 offen lds
	s_nop 3
	s_mov_b32 m0, s72
	s_nop 0
	buffer_load_dwordx4 v224, s[48:51], s97 offen lds
	s_nop 3
	s_mov_b32 m0, s73
	s_nop 0
	buffer_load_dwordx4 v225, s[48:51], s97 offen lds
	s_nop 3
	s_mov_b32 m0, s31
	s_nop 0
	buffer_load_dwordx4 v224, s[60:63], s36 offen lds
	s_nop 3
	s_mov_b32 m0, s74
	s_nop 0
	buffer_load_dwordx4 v225, s[60:63], s36 offen lds
	s_waitcnt vmcnt(8)
	s_waitcnt lgkmcnt(0)
	s_barrier
	s_waitcnt lgkmcnt(7)
	v_mfma_f32_16x16x32_bf16 v[60:63], v[152:155], v[184:187], v[60:63]
	v_mfma_f32_16x16x32_bf16 v[56:59], v[160:163], v[184:187], v[56:59]
	s_waitcnt lgkmcnt(5)
	v_mfma_f32_16x16x32_bf16 v[44:47], v[152:155], v[192:195], v[44:47]
	v_mfma_f32_16x16x32_bf16 v[40:43], v[160:163], v[192:195], v[40:43]
	s_waitcnt lgkmcnt(3)
	v_mfma_f32_16x16x32_bf16 v[28:31], v[152:155], v[200:203], v[28:31]
	v_mfma_f32_16x16x32_bf16 v[24:27], v[160:163], v[200:203], v[24:27]
	s_waitcnt lgkmcnt(1)
	v_mfma_f32_16x16x32_bf16 v[12:15], v[152:155], v[228:231], v[12:15]
	v_mfma_f32_16x16x32_bf16 v[8:11], v[160:163], v[228:231], v[8:11]
	v_mfma_f32_16x16x32_bf16 v[60:63], v[156:159], v[188:191], v[60:63]
	v_mfma_f32_16x16x32_bf16 v[56:59], v[164:167], v[188:191], v[56:59]
	v_mfma_f32_16x16x32_bf16 v[44:47], v[156:159], v[196:199], v[44:47]
	v_mfma_f32_16x16x32_bf16 v[40:43], v[164:167], v[196:199], v[40:43]
	v_mfma_f32_16x16x32_bf16 v[28:31], v[156:159], v[204:207], v[28:31]
	v_mfma_f32_16x16x32_bf16 v[24:27], v[164:167], v[204:207], v[24:27]
	s_waitcnt lgkmcnt(0)
	v_mfma_f32_16x16x32_bf16 v[12:15], v[156:159], v[240:243], v[12:15]
	v_mfma_f32_16x16x32_bf16 v[8:11], v[164:167], v[240:243], v[8:11]
	v_mfma_f32_16x16x32_bf16 v[52:55], v[168:171], v[184:187], v[52:55]
	v_mfma_f32_16x16x32_bf16 v[48:51], v[176:179], v[184:187], v[48:51]
	v_mfma_f32_16x16x32_bf16 v[36:39], v[168:171], v[192:195], v[36:39]
	v_mfma_f32_16x16x32_bf16 v[32:35], v[176:179], v[192:195], v[32:35]
	v_mfma_f32_16x16x32_bf16 v[20:23], v[168:171], v[200:203], v[20:23]
	v_mfma_f32_16x16x32_bf16 v[16:19], v[176:179], v[200:203], v[16:19]
	v_mfma_f32_16x16x32_bf16 v[4:7], v[168:171], v[228:231], v[4:7]
	v_mfma_f32_16x16x32_bf16 v[0:3], v[176:179], v[228:231], v[0:3]
	v_mfma_f32_16x16x32_bf16 v[52:55], v[172:175], v[188:191], v[52:55]
	v_mfma_f32_16x16x32_bf16 v[48:51], v[180:183], v[188:191], v[48:51]
	v_mfma_f32_16x16x32_bf16 v[36:39], v[172:175], v[196:199], v[36:39]
	v_mfma_f32_16x16x32_bf16 v[32:35], v[180:183], v[196:199], v[32:35]
	v_mfma_f32_16x16x32_bf16 v[20:23], v[172:175], v[204:207], v[20:23]
	v_mfma_f32_16x16x32_bf16 v[16:19], v[180:183], v[204:207], v[16:19]
	v_mfma_f32_16x16x32_bf16 v[4:7], v[172:175], v[240:243], v[4:7]
	v_mfma_f32_16x16x32_bf16 v[0:3], v[180:183], v[240:243], v[0:3]
	s_barrier
	v_add_u32_e32 v80, 0x18000, v226
	ds_read_b128 v[152:155], v80
	ds_read_b128 v[156:159], v80 offset:1024
	ds_read_b128 v[160:163], v80 offset:2048
	ds_read_b128 v[164:167], v80 offset:3072
	v_add_u32_e32 v80, 0x1c000, v226
	ds_read_b128 v[168:171], v80
	ds_read_b128 v[172:175], v80 offset:1024
	ds_read_b128 v[176:179], v80 offset:2048
	ds_read_b128 v[180:183], v80 offset:3072
	ds_read_b128 v[184:187], v227 offset:32768
	ds_read_b128 v[188:191], v227 offset:33792
	ds_read_b128 v[192:195], v227 offset:34816
	ds_read_b128 v[196:199], v227 offset:35840
	ds_read_b128 v[200:203], v227 offset:36864
	ds_read_b128 v[204:207], v227 offset:37888
	ds_read_b128 v[228:231], v227 offset:38912
	ds_read_b128 v[240:243], v227 offset:39936
	s_add_i32 s36, s36, 0x80000
	s_mov_b32 m0, s75
	s_nop 0
	buffer_load_dwordx4 v224, s[60:63], s36 offen lds
	s_nop 3
	s_mov_b32 m0, s76
	s_nop 0
	buffer_load_dwordx4 v225, s[60:63], s36 offen lds
	s_waitcnt vmcnt(8)
	s_waitcnt lgkmcnt(0)
	s_barrier
	s_waitcnt lgkmcnt(7)
	v_mfma_f32_16x16x32_bf16 v[148:151], v[152:155], v[184:187], v[148:151]
	v_mfma_f32_16x16x32_bf16 v[144:147], v[160:163], v[184:187], v[144:147]
	s_waitcnt lgkmcnt(5)
	v_mfma_f32_16x16x32_bf16 v[132:135], v[152:155], v[192:195], v[132:135]
	v_mfma_f32_16x16x32_bf16 v[128:131], v[160:163], v[192:195], v[128:131]
	s_waitcnt lgkmcnt(3)
	v_mfma_f32_16x16x32_bf16 v[116:119], v[152:155], v[200:203], v[116:119]
	v_mfma_f32_16x16x32_bf16 v[112:115], v[160:163], v[200:203], v[112:115]
	s_waitcnt lgkmcnt(1)
	v_mfma_f32_16x16x32_bf16 v[76:79], v[152:155], v[228:231], v[76:79]
	v_mfma_f32_16x16x32_bf16 v[72:75], v[160:163], v[228:231], v[72:75]
	v_mfma_f32_16x16x32_bf16 v[148:151], v[156:159], v[188:191], v[148:151]
	v_mfma_f32_16x16x32_bf16 v[144:147], v[164:167], v[188:191], v[144:147]
	v_mfma_f32_16x16x32_bf16 v[132:135], v[156:159], v[196:199], v[132:135]
	v_mfma_f32_16x16x32_bf16 v[128:131], v[164:167], v[196:199], v[128:131]
	v_mfma_f32_16x16x32_bf16 v[116:119], v[156:159], v[204:207], v[116:119]
	v_mfma_f32_16x16x32_bf16 v[112:115], v[164:167], v[204:207], v[112:115]
	s_waitcnt lgkmcnt(0)
	v_mfma_f32_16x16x32_bf16 v[76:79], v[156:159], v[240:243], v[76:79]
	v_mfma_f32_16x16x32_bf16 v[72:75], v[164:167], v[240:243], v[72:75]
	v_mfma_f32_16x16x32_bf16 v[140:143], v[168:171], v[184:187], v[140:143]
	v_mfma_f32_16x16x32_bf16 v[136:139], v[176:179], v[184:187], v[136:139]
	v_mfma_f32_16x16x32_bf16 v[124:127], v[168:171], v[192:195], v[124:127]
	v_mfma_f32_16x16x32_bf16 v[120:123], v[176:179], v[192:195], v[120:123]
	v_mfma_f32_16x16x32_bf16 v[108:111], v[168:171], v[200:203], v[108:111]
	v_mfma_f32_16x16x32_bf16 v[104:107], v[176:179], v[200:203], v[104:107]
	v_mfma_f32_16x16x32_bf16 v[68:71], v[168:171], v[228:231], v[68:71]
	v_mfma_f32_16x16x32_bf16 v[64:67], v[176:179], v[228:231], v[64:67]
	v_mfma_f32_16x16x32_bf16 v[140:143], v[172:175], v[188:191], v[140:143]
	v_mfma_f32_16x16x32_bf16 v[136:139], v[180:183], v[188:191], v[136:139]
	v_mfma_f32_16x16x32_bf16 v[124:127], v[172:175], v[196:199], v[124:127]
	v_mfma_f32_16x16x32_bf16 v[120:123], v[180:183], v[196:199], v[120:123]
	v_mfma_f32_16x16x32_bf16 v[108:111], v[172:175], v[204:207], v[108:111]
	v_mfma_f32_16x16x32_bf16 v[104:107], v[180:183], v[204:207], v[104:107]
	v_mfma_f32_16x16x32_bf16 v[68:71], v[172:175], v[240:243], v[68:71]
	v_mfma_f32_16x16x32_bf16 v[64:67], v[180:183], v[240:243], v[64:67]
	s_barrier
	ds_read_b128 v[184:187], v227 offset:49152
	ds_read_b128 v[188:191], v227 offset:50176
	ds_read_b128 v[192:195], v227 offset:51200
	ds_read_b128 v[196:199], v227 offset:52224
	ds_read_b128 v[200:203], v227 offset:53248
	ds_read_b128 v[204:207], v227 offset:54272
	ds_read_b128 v[228:231], v227 offset:55296
	ds_read_b128 v[240:243], v227 offset:56320
	s_or_b32 s36, s95, 0x4000
	s_mov_b32 m0, s77
	s_nop 0
	buffer_load_dwordx4 v224, s[48:51], s36 offen lds
	s_nop 3
	s_mov_b32 m0, s78
	s_nop 0
	buffer_load_dwordx4 v225, s[48:51], s36 offen lds
	s_add_i32 s36, s95, 0x84000
	s_mov_b32 m0, s83
	s_nop 0
	buffer_load_dwordx4 v224, s[48:51], s36 offen lds
	s_nop 3
	s_mov_b32 m0, s84
	s_nop 0
	buffer_load_dwordx4 v225, s[48:51], s36 offen lds
	s_nop 3
	s_mov_b32 m0, s79
	s_nop 0
	buffer_load_dwordx4 v224, s[60:63], s94 offen lds
	s_nop 3
	s_mov_b32 m0, s82
	s_nop 0
	buffer_load_dwordx4 v225, s[60:63], s94 offen lds
	s_waitcnt vmcnt(8)
	s_waitcnt lgkmcnt(0)
	s_barrier
	s_waitcnt lgkmcnt(7)
	v_mfma_f32_16x16x32_bf16 v[60:63], v[152:155], v[184:187], v[60:63]
	v_mfma_f32_16x16x32_bf16 v[56:59], v[160:163], v[184:187], v[56:59]
	s_waitcnt lgkmcnt(5)
	v_mfma_f32_16x16x32_bf16 v[44:47], v[152:155], v[192:195], v[44:47]
	v_mfma_f32_16x16x32_bf16 v[40:43], v[160:163], v[192:195], v[40:43]
	s_waitcnt lgkmcnt(3)
	v_mfma_f32_16x16x32_bf16 v[28:31], v[152:155], v[200:203], v[28:31]
	v_mfma_f32_16x16x32_bf16 v[24:27], v[160:163], v[200:203], v[24:27]
	s_waitcnt lgkmcnt(1)
	v_mfma_f32_16x16x32_bf16 v[12:15], v[152:155], v[228:231], v[12:15]
	v_mfma_f32_16x16x32_bf16 v[8:11], v[160:163], v[228:231], v[8:11]
	v_mfma_f32_16x16x32_bf16 v[60:63], v[156:159], v[188:191], v[60:63]
	v_mfma_f32_16x16x32_bf16 v[56:59], v[164:167], v[188:191], v[56:59]
	v_mfma_f32_16x16x32_bf16 v[44:47], v[156:159], v[196:199], v[44:47]
	v_mfma_f32_16x16x32_bf16 v[40:43], v[164:167], v[196:199], v[40:43]
	v_mfma_f32_16x16x32_bf16 v[28:31], v[156:159], v[204:207], v[28:31]
	v_mfma_f32_16x16x32_bf16 v[24:27], v[164:167], v[204:207], v[24:27]
	s_waitcnt lgkmcnt(0)
	v_mfma_f32_16x16x32_bf16 v[12:15], v[156:159], v[240:243], v[12:15]
	v_mfma_f32_16x16x32_bf16 v[8:11], v[164:167], v[240:243], v[8:11]
	v_mfma_f32_16x16x32_bf16 v[52:55], v[168:171], v[184:187], v[52:55]
	v_mfma_f32_16x16x32_bf16 v[48:51], v[176:179], v[184:187], v[48:51]
	v_mfma_f32_16x16x32_bf16 v[36:39], v[168:171], v[192:195], v[36:39]
	v_mfma_f32_16x16x32_bf16 v[32:35], v[176:179], v[192:195], v[32:35]
	v_mfma_f32_16x16x32_bf16 v[20:23], v[168:171], v[200:203], v[20:23]
	v_mfma_f32_16x16x32_bf16 v[16:19], v[176:179], v[200:203], v[16:19]
	v_mfma_f32_16x16x32_bf16 v[4:7], v[168:171], v[228:231], v[4:7]
	v_mfma_f32_16x16x32_bf16 v[0:3], v[176:179], v[228:231], v[0:3]
	v_mfma_f32_16x16x32_bf16 v[52:55], v[172:175], v[188:191], v[52:55]
	v_mfma_f32_16x16x32_bf16 v[48:51], v[180:183], v[188:191], v[48:51]
	v_mfma_f32_16x16x32_bf16 v[36:39], v[172:175], v[196:199], v[36:39]
	v_mfma_f32_16x16x32_bf16 v[32:35], v[180:183], v[196:199], v[32:35]
	v_mfma_f32_16x16x32_bf16 v[20:23], v[172:175], v[204:207], v[20:23]
	v_mfma_f32_16x16x32_bf16 v[16:19], v[180:183], v[204:207], v[16:19]
	v_mfma_f32_16x16x32_bf16 v[4:7], v[172:175], v[240:243], v[4:7]
	v_mfma_f32_16x16x32_bf16 v[0:3], v[180:183], v[240:243], v[0:3]
	s_barrier
	s_add_i32 s38, s38, 2
	s_add_i32 s39, s39, 0x8000
	s_cmp_gt_u32 s38, 29
	s_cbranch_scc1 .LBB0_597

.Lnb_p4:
	s_add_i32 s11, s8, 0xfff84000
	s_cmp_eq_u32 s10, 28
	s_cselect_b32 s13, s6, s11
	s_cselect_b32 s12, s7, s9
	s_or_b32 s11, s13, 0x4000
	s_mov_b32 m0, s89
	s_nop 0
	buffer_load_dwordx4 v220, s[64:67], s8 offen lds
	s_nop 3
	s_mov_b32 m0, s91
	s_nop 0
	buffer_load_dwordx4 v221, s[64:67], s8 offen lds
	s_waitcnt vmcnt(24)
	s_waitcnt lgkmcnt(0)
	s_barrier
	s_waitcnt lgkmcnt(7)
	v_mfma_f32_16x16x32_bf16 v[164:167], v[128:131], v[184:187], 0
	v_mfma_f32_16x16x32_bf16 v[160:163], v[152:155], v[184:187], 0
	s_waitcnt lgkmcnt(5)
	v_mfma_f32_16x16x32_bf16 v[136:139], v[128:131], v[192:195], 0
	v_mfma_f32_16x16x32_bf16 v[132:135], v[152:155], v[192:195], 0
	s_waitcnt lgkmcnt(3)
	v_mfma_f32_16x16x32_bf16 v[116:119], v[128:131], v[200:203], 0
	v_mfma_f32_16x16x32_bf16 v[112:115], v[152:155], v[200:203], 0
	s_waitcnt lgkmcnt(1)
	v_mfma_f32_16x16x32_bf16 v[76:79], v[128:131], v[224:227], 0
	v_mfma_f32_16x16x32_bf16 v[72:75], v[152:155], v[224:227], 0
	v_mfma_f32_16x16x32_bf16 v[164:167], v[140:143], v[188:191], v[164:167]
	v_mfma_f32_16x16x32_bf16 v[160:163], v[156:159], v[188:191], v[160:163]
	v_mfma_f32_16x16x32_bf16 v[136:139], v[140:143], v[196:199], v[136:139]
	v_mfma_f32_16x16x32_bf16 v[132:135], v[156:159], v[196:199], v[132:135]
	v_mfma_f32_16x16x32_bf16 v[116:119], v[140:143], v[204:207], v[116:119]
	v_mfma_f32_16x16x32_bf16 v[112:115], v[156:159], v[204:207], v[112:115]
	s_waitcnt lgkmcnt(0)
	v_mfma_f32_16x16x32_bf16 v[76:79], v[140:143], v[228:231], v[76:79]
	v_mfma_f32_16x16x32_bf16 v[72:75], v[156:159], v[228:231], v[72:75]
	v_mfma_f32_16x16x32_bf16 v[148:151], v[168:171], v[184:187], 0
	v_mfma_f32_16x16x32_bf16 v[144:147], v[176:179], v[184:187], 0
	v_mfma_f32_16x16x32_bf16 v[124:127], v[168:171], v[192:195], 0
	v_mfma_f32_16x16x32_bf16 v[120:123], v[176:179], v[192:195], 0
	v_mfma_f32_16x16x32_bf16 v[108:111], v[168:171], v[200:203], 0
	v_mfma_f32_16x16x32_bf16 v[104:107], v[176:179], v[200:203], 0
	v_mfma_f32_16x16x32_bf16 v[68:71], v[168:171], v[224:227], 0
	v_mfma_f32_16x16x32_bf16 v[64:67], v[176:179], v[224:227], 0
	v_mfma_f32_16x16x32_bf16 v[148:151], v[172:175], v[188:191], v[148:151]
	v_mfma_f32_16x16x32_bf16 v[144:147], v[180:183], v[188:191], v[144:147]
	v_mfma_f32_16x16x32_bf16 v[124:127], v[172:175], v[196:199], v[124:127]
	v_mfma_f32_16x16x32_bf16 v[120:123], v[180:183], v[196:199], v[120:123]
	v_mfma_f32_16x16x32_bf16 v[108:111], v[172:175], v[204:207], v[108:111]
	v_mfma_f32_16x16x32_bf16 v[104:107], v[180:183], v[204:207], v[104:107]
	v_mfma_f32_16x16x32_bf16 v[68:71], v[172:175], v[228:231], v[68:71]
	v_mfma_f32_16x16x32_bf16 v[64:67], v[180:183], v[228:231], v[64:67]
	s_barrier
	ds_read_b128 v[184:187], v223 offset:16384
	ds_read_b128 v[188:191], v223 offset:17408
	ds_read_b128 v[192:195], v223 offset:18432
	ds_read_b128 v[196:199], v223 offset:19456
	ds_read_b128 v[200:203], v223 offset:20480
	ds_read_b128 v[204:207], v223 offset:21504
	ds_read_b128 v[224:227], v223 offset:22528
	ds_read_b128 v[228:231], v223 offset:23552
	s_mov_b32 m0, s55
	s_nop 0
	buffer_load_dwordx4 v220, s[48:51], s12 offen lds
	s_add_i32 s14, s12, 0x80000
	s_mov_b32 m0, s76
	s_nop 0
	buffer_load_dwordx4 v221, s[48:51], s12 offen lds
	s_nop 3
	s_mov_b32 m0, s77
	s_nop 0
	buffer_load_dwordx4 v220, s[48:51], s14 offen lds
	s_nop 3
	s_mov_b32 m0, s78
	s_nop 0
	buffer_load_dwordx4 v221, s[48:51], s14 offen lds
	s_nop 3
	s_mov_b32 m0, s31
	s_nop 0
	buffer_load_dwordx4 v220, s[64:67], s13 offen lds
	s_nop 3
	s_mov_b32 m0, s79
	s_nop 0
	buffer_load_dwordx4 v221, s[64:67], s13 offen lds
	s_waitcnt vmcnt(24)
	s_waitcnt lgkmcnt(0)
	s_barrier
	s_waitcnt lgkmcnt(7)
	v_mfma_f32_16x16x32_bf16 v[60:63], v[128:131], v[184:187], 0
	v_mfma_f32_16x16x32_bf16 v[56:59], v[152:155], v[184:187], 0
	s_waitcnt lgkmcnt(5)
	v_mfma_f32_16x16x32_bf16 v[44:47], v[128:131], v[192:195], 0
	v_mfma_f32_16x16x32_bf16 v[40:43], v[152:155], v[192:195], 0
	s_waitcnt lgkmcnt(3)
	v_mfma_f32_16x16x32_bf16 v[28:31], v[128:131], v[200:203], 0
	v_mfma_f32_16x16x32_bf16 v[24:27], v[152:155], v[200:203], 0
	s_waitcnt lgkmcnt(1)
	v_mfma_f32_16x16x32_bf16 v[12:15], v[128:131], v[224:227], 0
	v_mfma_f32_16x16x32_bf16 v[8:11], v[152:155], v[224:227], 0
	v_mfma_f32_16x16x32_bf16 v[60:63], v[140:143], v[188:191], v[60:63]
	v_mfma_f32_16x16x32_bf16 v[56:59], v[156:159], v[188:191], v[56:59]
	v_mfma_f32_16x16x32_bf16 v[44:47], v[140:143], v[196:199], v[44:47]
	v_mfma_f32_16x16x32_bf16 v[40:43], v[156:159], v[196:199], v[40:43]
	v_mfma_f32_16x16x32_bf16 v[28:31], v[140:143], v[204:207], v[28:31]
	v_mfma_f32_16x16x32_bf16 v[24:27], v[156:159], v[204:207], v[24:27]
	s_waitcnt lgkmcnt(0)
	v_mfma_f32_16x16x32_bf16 v[12:15], v[140:143], v[228:231], v[12:15]
	v_mfma_f32_16x16x32_bf16 v[8:11], v[156:159], v[228:231], v[8:11]
	v_mfma_f32_16x16x32_bf16 v[52:55], v[168:171], v[184:187], 0
	v_mfma_f32_16x16x32_bf16 v[48:51], v[176:179], v[184:187], 0
	v_mfma_f32_16x16x32_bf16 v[36:39], v[168:171], v[192:195], 0
	v_mfma_f32_16x16x32_bf16 v[32:35], v[176:179], v[192:195], 0
	v_mfma_f32_16x16x32_bf16 v[20:23], v[168:171], v[200:203], 0
	v_mfma_f32_16x16x32_bf16 v[16:19], v[176:179], v[200:203], 0
	v_mfma_f32_16x16x32_bf16 v[4:7], v[168:171], v[224:227], 0
	v_mfma_f32_16x16x32_bf16 v[0:3], v[176:179], v[224:227], 0
	v_mfma_f32_16x16x32_bf16 v[52:55], v[172:175], v[188:191], v[52:55]
	v_mfma_f32_16x16x32_bf16 v[48:51], v[180:183], v[188:191], v[48:51]
	v_mfma_f32_16x16x32_bf16 v[36:39], v[172:175], v[196:199], v[36:39]
	v_mfma_f32_16x16x32_bf16 v[32:35], v[180:183], v[196:199], v[32:35]
	v_mfma_f32_16x16x32_bf16 v[20:23], v[172:175], v[204:207], v[20:23]
	v_mfma_f32_16x16x32_bf16 v[16:19], v[180:183], v[204:207], v[16:19]
	v_mfma_f32_16x16x32_bf16 v[4:7], v[172:175], v[228:231], v[4:7]
	v_mfma_f32_16x16x32_bf16 v[0:3], v[180:183], v[228:231], v[0:3]
	s_barrier
	v_add_u32_e32 v156, 0x18000, v222
	v_add_u32_e32 v180, 0x1c000, v222
	ds_read_b128 v[128:131], v156
	ds_read_b128 v[140:143], v156 offset:1024
	ds_read_b128 v[152:155], v156 offset:2048
	ds_read_b128 v[156:159], v156 offset:3072
	ds_read_b128 v[168:171], v180
	ds_read_b128 v[172:175], v180 offset:1024
	ds_read_b128 v[176:179], v180 offset:2048
	ds_read_b128 v[180:183], v180 offset:3072
	ds_read_b128 v[184:187], v223 offset:32768
	ds_read_b128 v[188:191], v223 offset:33792
	ds_read_b128 v[192:195], v223 offset:34816
	ds_read_b128 v[196:199], v223 offset:35840
	ds_read_b128 v[200:203], v223 offset:36864
	ds_read_b128 v[204:207], v223 offset:37888
	ds_read_b128 v[224:227], v223 offset:38912
	ds_read_b128 v[228:231], v223 offset:39936
	s_add_i32 s13, s13, 0x80000
	s_mov_b32 m0, s82
	s_nop 0
	buffer_load_dwordx4 v220, s[64:67], s13 offen lds
	s_nop 3
	s_mov_b32 m0, s83
	s_nop 0
	buffer_load_dwordx4 v221, s[64:67], s13 offen lds
	s_waitcnt vmcnt(8)
	s_waitcnt lgkmcnt(0)
	s_barrier
	s_waitcnt lgkmcnt(7)
	v_mfma_f32_16x16x32_bf16 v[164:167], v[128:131], v[184:187], v[164:167]
	v_mfma_f32_16x16x32_bf16 v[160:163], v[152:155], v[184:187], v[160:163]
	s_waitcnt lgkmcnt(5)
	v_mfma_f32_16x16x32_bf16 v[136:139], v[128:131], v[192:195], v[136:139]
	v_mfma_f32_16x16x32_bf16 v[132:135], v[152:155], v[192:195], v[132:135]
	s_waitcnt lgkmcnt(3)
	v_mfma_f32_16x16x32_bf16 v[116:119], v[128:131], v[200:203], v[116:119]
	v_mfma_f32_16x16x32_bf16 v[112:115], v[152:155], v[200:203], v[112:115]
	s_waitcnt lgkmcnt(1)
	v_mfma_f32_16x16x32_bf16 v[76:79], v[128:131], v[224:227], v[76:79]
	v_mfma_f32_16x16x32_bf16 v[72:75], v[152:155], v[224:227], v[72:75]
	v_mfma_f32_16x16x32_bf16 v[164:167], v[140:143], v[188:191], v[164:167]
	v_mfma_f32_16x16x32_bf16 v[160:163], v[156:159], v[188:191], v[160:163]
	v_mfma_f32_16x16x32_bf16 v[136:139], v[140:143], v[196:199], v[136:139]
	v_mfma_f32_16x16x32_bf16 v[132:135], v[156:159], v[196:199], v[132:135]
	v_mfma_f32_16x16x32_bf16 v[116:119], v[140:143], v[204:207], v[116:119]
	v_mfma_f32_16x16x32_bf16 v[112:115], v[156:159], v[204:207], v[112:115]
	s_waitcnt lgkmcnt(0)
	v_mfma_f32_16x16x32_bf16 v[76:79], v[140:143], v[228:231], v[76:79]
	v_mfma_f32_16x16x32_bf16 v[72:75], v[156:159], v[228:231], v[72:75]
	v_mfma_f32_16x16x32_bf16 v[148:151], v[168:171], v[184:187], v[148:151]
	v_mfma_f32_16x16x32_bf16 v[144:147], v[176:179], v[184:187], v[144:147]
	v_mfma_f32_16x16x32_bf16 v[124:127], v[168:171], v[192:195], v[124:127]
	v_mfma_f32_16x16x32_bf16 v[120:123], v[176:179], v[192:195], v[120:123]
	v_mfma_f32_16x16x32_bf16 v[108:111], v[168:171], v[200:203], v[108:111]
	v_mfma_f32_16x16x32_bf16 v[104:107], v[176:179], v[200:203], v[104:107]
	v_mfma_f32_16x16x32_bf16 v[68:71], v[168:171], v[224:227], v[68:71]
	v_mfma_f32_16x16x32_bf16 v[64:67], v[176:179], v[224:227], v[64:67]
	v_mfma_f32_16x16x32_bf16 v[148:151], v[172:175], v[188:191], v[148:151]
	v_mfma_f32_16x16x32_bf16 v[144:147], v[180:183], v[188:191], v[144:147]
	v_mfma_f32_16x16x32_bf16 v[124:127], v[172:175], v[196:199], v[124:127]
	v_mfma_f32_16x16x32_bf16 v[120:123], v[180:183], v[196:199], v[120:123]
	v_mfma_f32_16x16x32_bf16 v[108:111], v[172:175], v[204:207], v[108:111]
	v_mfma_f32_16x16x32_bf16 v[104:107], v[180:183], v[204:207], v[104:107]
	v_mfma_f32_16x16x32_bf16 v[68:71], v[172:175], v[228:231], v[68:71]
	v_mfma_f32_16x16x32_bf16 v[64:67], v[180:183], v[228:231], v[64:67]
	s_barrier
	ds_read_b128 v[184:187], v223 offset:49152
	ds_read_b128 v[188:191], v223 offset:50176
	ds_read_b128 v[192:195], v223 offset:51200
	ds_read_b128 v[196:199], v223 offset:52224
	ds_read_b128 v[200:203], v223 offset:53248
	ds_read_b128 v[204:207], v223 offset:54272
	ds_read_b128 v[224:227], v223 offset:55296
	ds_read_b128 v[228:231], v223 offset:56320
	s_or_b32 s13, s12, 0x4000
	s_mov_b32 m0, s34
	s_nop 0
	buffer_load_dwordx4 v220, s[48:51], s13 offen lds
	s_add_i32 s12, s12, 0x84000
	s_mov_b32 m0, s84
	s_nop 0
	buffer_load_dwordx4 v221, s[48:51], s13 offen lds
	s_nop 3
	s_mov_b32 m0, s87
	s_nop 0
	buffer_load_dwordx4 v220, s[48:51], s12 offen lds
	s_nop 3
	s_mov_b32 m0, s88
	s_nop 0
	buffer_load_dwordx4 v221, s[48:51], s12 offen lds
	s_nop 3
	s_mov_b32 m0, s85
	s_nop 0
	buffer_load_dwordx4 v220, s[64:67], s11 offen lds
	s_nop 3
	s_mov_b32 m0, s86
	s_nop 0
	buffer_load_dwordx4 v221, s[64:67], s11 offen lds
	s_waitcnt vmcnt(8)
	s_waitcnt lgkmcnt(0)
	s_barrier
	s_waitcnt lgkmcnt(7)
	v_mfma_f32_16x16x32_bf16 v[60:63], v[128:131], v[184:187], v[60:63]
	v_mfma_f32_16x16x32_bf16 v[56:59], v[152:155], v[184:187], v[56:59]
	s_waitcnt lgkmcnt(5)
	v_mfma_f32_16x16x32_bf16 v[44:47], v[128:131], v[192:195], v[44:47]
	v_mfma_f32_16x16x32_bf16 v[40:43], v[152:155], v[192:195], v[40:43]
	s_waitcnt lgkmcnt(3)
	v_mfma_f32_16x16x32_bf16 v[28:31], v[128:131], v[200:203], v[28:31]
	v_mfma_f32_16x16x32_bf16 v[24:27], v[152:155], v[200:203], v[24:27]
	s_waitcnt lgkmcnt(1)
	v_mfma_f32_16x16x32_bf16 v[12:15], v[128:131], v[224:227], v[12:15]
	v_mfma_f32_16x16x32_bf16 v[8:11], v[152:155], v[224:227], v[8:11]
	v_mfma_f32_16x16x32_bf16 v[60:63], v[140:143], v[188:191], v[60:63]
	v_mfma_f32_16x16x32_bf16 v[56:59], v[156:159], v[188:191], v[56:59]
	v_mfma_f32_16x16x32_bf16 v[44:47], v[140:143], v[196:199], v[44:47]
	v_mfma_f32_16x16x32_bf16 v[40:43], v[156:159], v[196:199], v[40:43]
	v_mfma_f32_16x16x32_bf16 v[28:31], v[140:143], v[204:207], v[28:31]
	v_mfma_f32_16x16x32_bf16 v[24:27], v[156:159], v[204:207], v[24:27]
	s_waitcnt lgkmcnt(0)
	v_mfma_f32_16x16x32_bf16 v[12:15], v[140:143], v[228:231], v[12:15]
	v_mfma_f32_16x16x32_bf16 v[8:11], v[156:159], v[228:231], v[8:11]
	v_mfma_f32_16x16x32_bf16 v[52:55], v[168:171], v[184:187], v[52:55]
	v_mfma_f32_16x16x32_bf16 v[48:51], v[176:179], v[184:187], v[48:51]
	v_mfma_f32_16x16x32_bf16 v[36:39], v[168:171], v[192:195], v[36:39]
	v_mfma_f32_16x16x32_bf16 v[32:35], v[176:179], v[192:195], v[32:35]
	v_mfma_f32_16x16x32_bf16 v[20:23], v[168:171], v[200:203], v[20:23]
	v_mfma_f32_16x16x32_bf16 v[16:19], v[176:179], v[200:203], v[16:19]
	v_mfma_f32_16x16x32_bf16 v[4:7], v[168:171], v[224:227], v[4:7]
	v_mfma_f32_16x16x32_bf16 v[0:3], v[176:179], v[224:227], v[0:3]
	v_mfma_f32_16x16x32_bf16 v[52:55], v[172:175], v[188:191], v[52:55]
	v_mfma_f32_16x16x32_bf16 v[48:51], v[180:183], v[188:191], v[48:51]
	v_mfma_f32_16x16x32_bf16 v[36:39], v[172:175], v[196:199], v[36:39]
	v_mfma_f32_16x16x32_bf16 v[32:35], v[180:183], v[196:199], v[32:35]
	v_mfma_f32_16x16x32_bf16 v[20:23], v[172:175], v[204:207], v[20:23]
	v_mfma_f32_16x16x32_bf16 v[16:19], v[180:183], v[204:207], v[16:19]
	v_mfma_f32_16x16x32_bf16 v[4:7], v[172:175], v[228:231], v[4:7]
	v_mfma_f32_16x16x32_bf16 v[0:3], v[180:183], v[228:231], v[0:3]
	s_barrier
	s_add_i32 s10, s10, 2
	s_add_i32 s8, s8, 0x8000
	s_add_i32 s9, s9, 0x8000
.LBB0_691:
	v_add_u32_e32 v156, 0x10000, v222
	v_add_u32_e32 v180, 0x14000, v222
	ds_read_b128 v[128:131], v156
	ds_read_b128 v[140:143], v156 offset:1024
	ds_read_b128 v[152:155], v156 offset:2048
	ds_read_b128 v[156:159], v156 offset:3072
	ds_read_b128 v[168:171], v180
	ds_read_b128 v[172:175], v180 offset:1024
	ds_read_b128 v[176:179], v180 offset:2048
	ds_read_b128 v[180:183], v180 offset:3072
	s_add_i32 s11, s8, 0xfff84000
	s_cmp_eq_u32 s10, 28
	s_cselect_b32 s13, s6, s11
	s_cselect_b32 s12, s7, s9
	s_or_b32 s11, s13, 0x4000
	ds_read_b128 v[184:187], v223
	ds_read_b128 v[188:191], v223 offset:1024
	ds_read_b128 v[192:195], v223 offset:2048
	ds_read_b128 v[196:199], v223 offset:3072
	ds_read_b128 v[200:203], v223 offset:4096
	ds_read_b128 v[204:207], v223 offset:5120
	ds_read_b128 v[224:227], v223 offset:6144
	ds_read_b128 v[228:231], v223 offset:7168
	s_mov_b32 m0, s89
	s_nop 0
	buffer_load_dwordx4 v220, s[64:67], s8 offen lds
	s_nop 3
	s_mov_b32 m0, s91
	s_nop 0
	buffer_load_dwordx4 v221, s[64:67], s8 offen lds
	s_waitcnt vmcnt(8)
	s_waitcnt lgkmcnt(0)
	s_barrier
	s_waitcnt lgkmcnt(7)
	v_mfma_f32_16x16x32_bf16 v[164:167], v[128:131], v[184:187], v[164:167]
	v_mfma_f32_16x16x32_bf16 v[160:163], v[152:155], v[184:187], v[160:163]
	s_waitcnt lgkmcnt(5)
	v_mfma_f32_16x16x32_bf16 v[136:139], v[128:131], v[192:195], v[136:139]
	v_mfma_f32_16x16x32_bf16 v[132:135], v[152:155], v[192:195], v[132:135]
	s_waitcnt lgkmcnt(3)
	v_mfma_f32_16x16x32_bf16 v[116:119], v[128:131], v[200:203], v[116:119]
	v_mfma_f32_16x16x32_bf16 v[112:115], v[152:155], v[200:203], v[112:115]
	s_waitcnt lgkmcnt(1)
	v_mfma_f32_16x16x32_bf16 v[76:79], v[128:131], v[224:227], v[76:79]
	v_mfma_f32_16x16x32_bf16 v[72:75], v[152:155], v[224:227], v[72:75]
	v_mfma_f32_16x16x32_bf16 v[164:167], v[140:143], v[188:191], v[164:167]
	v_mfma_f32_16x16x32_bf16 v[160:163], v[156:159], v[188:191], v[160:163]
	v_mfma_f32_16x16x32_bf16 v[136:139], v[140:143], v[196:199], v[136:139]
	v_mfma_f32_16x16x32_bf16 v[132:135], v[156:159], v[196:199], v[132:135]
	v_mfma_f32_16x16x32_bf16 v[116:119], v[140:143], v[204:207], v[116:119]
	v_mfma_f32_16x16x32_bf16 v[112:115], v[156:159], v[204:207], v[112:115]
	s_waitcnt lgkmcnt(0)
	v_mfma_f32_16x16x32_bf16 v[76:79], v[140:143], v[228:231], v[76:79]
	v_mfma_f32_16x16x32_bf16 v[72:75], v[156:159], v[228:231], v[72:75]
	v_mfma_f32_16x16x32_bf16 v[148:151], v[168:171], v[184:187], v[148:151]
	v_mfma_f32_16x16x32_bf16 v[144:147], v[176:179], v[184:187], v[144:147]
	v_mfma_f32_16x16x32_bf16 v[124:127], v[168:171], v[192:195], v[124:127]
	v_mfma_f32_16x16x32_bf16 v[120:123], v[176:179], v[192:195], v[120:123]
	v_mfma_f32_16x16x32_bf16 v[108:111], v[168:171], v[200:203], v[108:111]
	v_mfma_f32_16x16x32_bf16 v[104:107], v[176:179], v[200:203], v[104:107]
	v_mfma_f32_16x16x32_bf16 v[68:71], v[168:171], v[224:227], v[68:71]
	v_mfma_f32_16x16x32_bf16 v[64:67], v[176:179], v[224:227], v[64:67]
	v_mfma_f32_16x16x32_bf16 v[148:151], v[172:175], v[188:191], v[148:151]
	v_mfma_f32_16x16x32_bf16 v[144:147], v[180:183], v[188:191], v[144:147]
	v_mfma_f32_16x16x32_bf16 v[124:127], v[172:175], v[196:199], v[124:127]
	v_mfma_f32_16x16x32_bf16 v[120:123], v[180:183], v[196:199], v[120:123]
	v_mfma_f32_16x16x32_bf16 v[108:111], v[172:175], v[204:207], v[108:111]
	v_mfma_f32_16x16x32_bf16 v[104:107], v[180:183], v[204:207], v[104:107]
	v_mfma_f32_16x16x32_bf16 v[68:71], v[172:175], v[228:231], v[68:71]
	v_mfma_f32_16x16x32_bf16 v[64:67], v[180:183], v[228:231], v[64:67]
	s_barrier
	ds_read_b128 v[184:187], v223 offset:16384
	ds_read_b128 v[188:191], v223 offset:17408
	ds_read_b128 v[192:195], v223 offset:18432
	ds_read_b128 v[196:199], v223 offset:19456
	ds_read_b128 v[200:203], v223 offset:20480
	ds_read_b128 v[204:207], v223 offset:21504
	ds_read_b128 v[224:227], v223 offset:22528
	ds_read_b128 v[228:231], v223 offset:23552
	s_mov_b32 m0, s55
	s_nop 0
	buffer_load_dwordx4 v220, s[48:51], s12 offen lds
	s_add_i32 s14, s12, 0x80000
	s_mov_b32 m0, s76
	s_nop 0
	buffer_load_dwordx4 v221, s[48:51], s12 offen lds
	s_nop 3
	s_mov_b32 m0, s77
	s_nop 0
	buffer_load_dwordx4 v220, s[48:51], s14 offen lds
	s_nop 3
	s_mov_b32 m0, s78
	s_nop 0
	buffer_load_dwordx4 v221, s[48:51], s14 offen lds
	s_nop 3
	s_mov_b32 m0, s31
	s_nop 0
	buffer_load_dwordx4 v220, s[64:67], s13 offen lds
	s_nop 3
	s_mov_b32 m0, s79
	s_nop 0
	buffer_load_dwordx4 v221, s[64:67], s13 offen lds
	s_waitcnt vmcnt(8)
	s_waitcnt lgkmcnt(0)
	s_barrier
	s_waitcnt lgkmcnt(7)
	v_mfma_f32_16x16x32_bf16 v[60:63], v[128:131], v[184:187], v[60:63]
	v_mfma_f32_16x16x32_bf16 v[56:59], v[152:155], v[184:187], v[56:59]
	s_waitcnt lgkmcnt(5)
	v_mfma_f32_16x16x32_bf16 v[44:47], v[128:131], v[192:195], v[44:47]
	v_mfma_f32_16x16x32_bf16 v[40:43], v[152:155], v[192:195], v[40:43]
	s_waitcnt lgkmcnt(3)
	v_mfma_f32_16x16x32_bf16 v[28:31], v[128:131], v[200:203], v[28:31]
	v_mfma_f32_16x16x32_bf16 v[24:27], v[152:155], v[200:203], v[24:27]
	s_waitcnt lgkmcnt(1)
	v_mfma_f32_16x16x32_bf16 v[12:15], v[128:131], v[224:227], v[12:15]
	v_mfma_f32_16x16x32_bf16 v[8:11], v[152:155], v[224:227], v[8:11]
	v_mfma_f32_16x16x32_bf16 v[60:63], v[140:143], v[188:191], v[60:63]
	v_mfma_f32_16x16x32_bf16 v[56:59], v[156:159], v[188:191], v[56:59]
	v_mfma_f32_16x16x32_bf16 v[44:47], v[140:143], v[196:199], v[44:47]
	v_mfma_f32_16x16x32_bf16 v[40:43], v[156:159], v[196:199], v[40:43]
	v_mfma_f32_16x16x32_bf16 v[28:31], v[140:143], v[204:207], v[28:31]
	v_mfma_f32_16x16x32_bf16 v[24:27], v[156:159], v[204:207], v[24:27]
	s_waitcnt lgkmcnt(0)
	v_mfma_f32_16x16x32_bf16 v[12:15], v[140:143], v[228:231], v[12:15]
	v_mfma_f32_16x16x32_bf16 v[8:11], v[156:159], v[228:231], v[8:11]
	v_mfma_f32_16x16x32_bf16 v[52:55], v[168:171], v[184:187], v[52:55]
	v_mfma_f32_16x16x32_bf16 v[48:51], v[176:179], v[184:187], v[48:51]
	v_mfma_f32_16x16x32_bf16 v[36:39], v[168:171], v[192:195], v[36:39]
	v_mfma_f32_16x16x32_bf16 v[32:35], v[176:179], v[192:195], v[32:35]
	v_mfma_f32_16x16x32_bf16 v[20:23], v[168:171], v[200:203], v[20:23]
	v_mfma_f32_16x16x32_bf16 v[16:19], v[176:179], v[200:203], v[16:19]
	v_mfma_f32_16x16x32_bf16 v[4:7], v[168:171], v[224:227], v[4:7]
	v_mfma_f32_16x16x32_bf16 v[0:3], v[176:179], v[224:227], v[0:3]
	v_mfma_f32_16x16x32_bf16 v[52:55], v[172:175], v[188:191], v[52:55]
	v_mfma_f32_16x16x32_bf16 v[48:51], v[180:183], v[188:191], v[48:51]
	v_mfma_f32_16x16x32_bf16 v[36:39], v[172:175], v[196:199], v[36:39]
	v_mfma_f32_16x16x32_bf16 v[32:35], v[180:183], v[196:199], v[32:35]
	v_mfma_f32_16x16x32_bf16 v[20:23], v[172:175], v[204:207], v[20:23]
	v_mfma_f32_16x16x32_bf16 v[16:19], v[180:183], v[204:207], v[16:19]
	v_mfma_f32_16x16x32_bf16 v[4:7], v[172:175], v[228:231], v[4:7]
	v_mfma_f32_16x16x32_bf16 v[0:3], v[180:183], v[228:231], v[0:3]
	s_barrier
	v_add_u32_e32 v156, 0x18000, v222
	v_add_u32_e32 v180, 0x1c000, v222
	ds_read_b128 v[128:131], v156
	ds_read_b128 v[140:143], v156 offset:1024
	ds_read_b128 v[152:155], v156 offset:2048
	ds_read_b128 v[156:159], v156 offset:3072
	ds_read_b128 v[168:171], v180
	ds_read_b128 v[172:175], v180 offset:1024
	ds_read_b128 v[176:179], v180 offset:2048
	ds_read_b128 v[180:183], v180 offset:3072
	ds_read_b128 v[184:187], v223 offset:32768
	ds_read_b128 v[188:191], v223 offset:33792
	ds_read_b128 v[192:195], v223 offset:34816
	ds_read_b128 v[196:199], v223 offset:35840
	ds_read_b128 v[200:203], v223 offset:36864
	ds_read_b128 v[204:207], v223 offset:37888
	ds_read_b128 v[224:227], v223 offset:38912
	ds_read_b128 v[228:231], v223 offset:39936
	s_add_i32 s13, s13, 0x80000
	s_mov_b32 m0, s82
	s_nop 0
	buffer_load_dwordx4 v220, s[64:67], s13 offen lds
	s_nop 3
	s_mov_b32 m0, s83
	s_nop 0
	buffer_load_dwordx4 v221, s[64:67], s13 offen lds
	s_waitcnt vmcnt(8)
	s_waitcnt lgkmcnt(0)
	s_barrier
	s_waitcnt lgkmcnt(7)
	v_mfma_f32_16x16x32_bf16 v[164:167], v[128:131], v[184:187], v[164:167]
	v_mfma_f32_16x16x32_bf16 v[160:163], v[152:155], v[184:187], v[160:163]
	s_waitcnt lgkmcnt(5)
	v_mfma_f32_16x16x32_bf16 v[136:139], v[128:131], v[192:195], v[136:139]
	v_mfma_f32_16x16x32_bf16 v[132:135], v[152:155], v[192:195], v[132:135]
	s_waitcnt lgkmcnt(3)
	v_mfma_f32_16x16x32_bf16 v[116:119], v[128:131], v[200:203], v[116:119]
	v_mfma_f32_16x16x32_bf16 v[112:115], v[152:155], v[200:203], v[112:115]
	s_waitcnt lgkmcnt(1)
	v_mfma_f32_16x16x32_bf16 v[76:79], v[128:131], v[224:227], v[76:79]
	v_mfma_f32_16x16x32_bf16 v[72:75], v[152:155], v[224:227], v[72:75]
	v_mfma_f32_16x16x32_bf16 v[164:167], v[140:143], v[188:191], v[164:167]
	v_mfma_f32_16x16x32_bf16 v[160:163], v[156:159], v[188:191], v[160:163]
	v_mfma_f32_16x16x32_bf16 v[136:139], v[140:143], v[196:199], v[136:139]
	v_mfma_f32_16x16x32_bf16 v[132:135], v[156:159], v[196:199], v[132:135]
	v_mfma_f32_16x16x32_bf16 v[116:119], v[140:143], v[204:207], v[116:119]
	v_mfma_f32_16x16x32_bf16 v[112:115], v[156:159], v[204:207], v[112:115]
	s_waitcnt lgkmcnt(0)
	v_mfma_f32_16x16x32_bf16 v[76:79], v[140:143], v[228:231], v[76:79]
	v_mfma_f32_16x16x32_bf16 v[72:75], v[156:159], v[228:231], v[72:75]
	v_mfma_f32_16x16x32_bf16 v[148:151], v[168:171], v[184:187], v[148:151]
	v_mfma_f32_16x16x32_bf16 v[144:147], v[176:179], v[184:187], v[144:147]
	v_mfma_f32_16x16x32_bf16 v[124:127], v[168:171], v[192:195], v[124:127]
	v_mfma_f32_16x16x32_bf16 v[120:123], v[176:179], v[192:195], v[120:123]
	v_mfma_f32_16x16x32_bf16 v[108:111], v[168:171], v[200:203], v[108:111]
	v_mfma_f32_16x16x32_bf16 v[104:107], v[176:179], v[200:203], v[104:107]
	v_mfma_f32_16x16x32_bf16 v[68:71], v[168:171], v[224:227], v[68:71]
	v_mfma_f32_16x16x32_bf16 v[64:67], v[176:179], v[224:227], v[64:67]
	v_mfma_f32_16x16x32_bf16 v[148:151], v[172:175], v[188:191], v[148:151]
	v_mfma_f32_16x16x32_bf16 v[144:147], v[180:183], v[188:191], v[144:147]
	v_mfma_f32_16x16x32_bf16 v[124:127], v[172:175], v[196:199], v[124:127]
	v_mfma_f32_16x16x32_bf16 v[120:123], v[180:183], v[196:199], v[120:123]
	v_mfma_f32_16x16x32_bf16 v[108:111], v[172:175], v[204:207], v[108:111]
	v_mfma_f32_16x16x32_bf16 v[104:107], v[180:183], v[204:207], v[104:107]
	v_mfma_f32_16x16x32_bf16 v[68:71], v[172:175], v[228:231], v[68:71]
	v_mfma_f32_16x16x32_bf16 v[64:67], v[180:183], v[228:231], v[64:67]
	s_barrier
	ds_read_b128 v[184:187], v223 offset:49152
	ds_read_b128 v[188:191], v223 offset:50176
	ds_read_b128 v[192:195], v223 offset:51200
	ds_read_b128 v[196:199], v223 offset:52224
	ds_read_b128 v[200:203], v223 offset:53248
	ds_read_b128 v[204:207], v223 offset:54272
	ds_read_b128 v[224:227], v223 offset:55296
	ds_read_b128 v[228:231], v223 offset:56320
	s_or_b32 s13, s12, 0x4000
	s_mov_b32 m0, s34
	s_nop 0
	buffer_load_dwordx4 v220, s[48:51], s13 offen lds
	s_add_i32 s12, s12, 0x84000
	s_mov_b32 m0, s84
	s_nop 0
	buffer_load_dwordx4 v221, s[48:51], s13 offen lds
	s_nop 3
	s_mov_b32 m0, s87
	s_nop 0
	buffer_load_dwordx4 v220, s[48:51], s12 offen lds
	s_nop 3
	s_mov_b32 m0, s88
	s_nop 0
	buffer_load_dwordx4 v221, s[48:51], s12 offen lds
	s_nop 3
	s_mov_b32 m0, s85
	s_nop 0
	buffer_load_dwordx4 v220, s[64:67], s11 offen lds
	s_nop 3
	s_mov_b32 m0, s86
	s_nop 0
	buffer_load_dwordx4 v221, s[64:67], s11 offen lds
	s_waitcnt vmcnt(8)
	s_waitcnt lgkmcnt(0)
	s_barrier
	s_waitcnt lgkmcnt(7)
	v_mfma_f32_16x16x32_bf16 v[60:63], v[128:131], v[184:187], v[60:63]
	v_mfma_f32_16x16x32_bf16 v[56:59], v[152:155], v[184:187], v[56:59]
	s_waitcnt lgkmcnt(5)
	v_mfma_f32_16x16x32_bf16 v[44:47], v[128:131], v[192:195], v[44:47]
	v_mfma_f32_16x16x32_bf16 v[40:43], v[152:155], v[192:195], v[40:43]
	s_waitcnt lgkmcnt(3)
	v_mfma_f32_16x16x32_bf16 v[28:31], v[128:131], v[200:203], v[28:31]
	v_mfma_f32_16x16x32_bf16 v[24:27], v[152:155], v[200:203], v[24:27]
	s_waitcnt lgkmcnt(1)
	v_mfma_f32_16x16x32_bf16 v[12:15], v[128:131], v[224:227], v[12:15]
	v_mfma_f32_16x16x32_bf16 v[8:11], v[152:155], v[224:227], v[8:11]
	v_mfma_f32_16x16x32_bf16 v[60:63], v[140:143], v[188:191], v[60:63]
	v_mfma_f32_16x16x32_bf16 v[56:59], v[156:159], v[188:191], v[56:59]
	v_mfma_f32_16x16x32_bf16 v[44:47], v[140:143], v[196:199], v[44:47]
	v_mfma_f32_16x16x32_bf16 v[40:43], v[156:159], v[196:199], v[40:43]
	v_mfma_f32_16x16x32_bf16 v[28:31], v[140:143], v[204:207], v[28:31]
	v_mfma_f32_16x16x32_bf16 v[24:27], v[156:159], v[204:207], v[24:27]
	s_waitcnt lgkmcnt(0)
	v_mfma_f32_16x16x32_bf16 v[12:15], v[140:143], v[228:231], v[12:15]
	v_mfma_f32_16x16x32_bf16 v[8:11], v[156:159], v[228:231], v[8:11]
	v_mfma_f32_16x16x32_bf16 v[52:55], v[168:171], v[184:187], v[52:55]
	v_mfma_f32_16x16x32_bf16 v[48:51], v[176:179], v[184:187], v[48:51]
	v_mfma_f32_16x16x32_bf16 v[36:39], v[168:171], v[192:195], v[36:39]
	v_mfma_f32_16x16x32_bf16 v[32:35], v[176:179], v[192:195], v[32:35]
	v_mfma_f32_16x16x32_bf16 v[20:23], v[168:171], v[200:203], v[20:23]
	v_mfma_f32_16x16x32_bf16 v[16:19], v[176:179], v[200:203], v[16:19]
	v_mfma_f32_16x16x32_bf16 v[4:7], v[168:171], v[224:227], v[4:7]
	v_mfma_f32_16x16x32_bf16 v[0:3], v[176:179], v[224:227], v[0:3]
	v_mfma_f32_16x16x32_bf16 v[52:55], v[172:175], v[188:191], v[52:55]
	v_mfma_f32_16x16x32_bf16 v[48:51], v[180:183], v[188:191], v[48:51]
	v_mfma_f32_16x16x32_bf16 v[36:39], v[172:175], v[196:199], v[36:39]
	v_mfma_f32_16x16x32_bf16 v[32:35], v[180:183], v[196:199], v[32:35]
	v_mfma_f32_16x16x32_bf16 v[20:23], v[172:175], v[204:207], v[20:23]
	v_mfma_f32_16x16x32_bf16 v[16:19], v[180:183], v[204:207], v[16:19]
	v_mfma_f32_16x16x32_bf16 v[4:7], v[172:175], v[228:231], v[4:7]
	v_mfma_f32_16x16x32_bf16 v[0:3], v[180:183], v[228:231], v[0:3]
	s_barrier
	s_add_i32 s10, s10, 2
	s_add_i32 s8, s8, 0x8000
	s_add_i32 s9, s9, 0x8000
	s_cmp_gt_u32 s10, 29
	s_cbranch_scc0 .LBB0_691

.Lnb_p5:
	s_add_i32 s53, s37, 0xfff84000
	s_cmp_eq_u32 s52, 28
	s_cselect_b32 s56, s4, s53
	s_cselect_b32 s55, s5, s51
	s_or_b32 s53, s56, 0x4000
	s_mov_b32 m0, s41
	s_nop 0
	buffer_load_dwordx4 v166, s[24:27], s37 offen lds
	s_nop 3
	s_mov_b32 m0, s42
	s_nop 0
	buffer_load_dwordx4 v167, s[24:27], s37 offen lds
	s_waitcnt vmcnt(24)
	s_waitcnt lgkmcnt(0)
	s_barrier
	s_waitcnt lgkmcnt(7)
	v_mfma_f32_16x16x32_bf16 v[148:151], v[152:155], v[190:193], 0
	v_mfma_f32_16x16x32_bf16 v[140:143], v[160:163], v[190:193], 0
	s_waitcnt lgkmcnt(5)
	v_mfma_f32_16x16x32_bf16 v[132:135], v[152:155], v[198:201], 0
	v_mfma_f32_16x16x32_bf16 v[124:127], v[160:163], v[198:201], 0
	s_waitcnt lgkmcnt(3)
	v_mfma_f32_16x16x32_bf16 v[116:119], v[152:155], v[220:223], 0
	v_mfma_f32_16x16x32_bf16 v[108:111], v[160:163], v[220:223], 0
	s_waitcnt lgkmcnt(1)
	v_mfma_f32_16x16x32_bf16 v[76:79], v[152:155], v[228:231], 0
	v_mfma_f32_16x16x32_bf16 v[68:71], v[160:163], v[228:231], 0
	v_mfma_f32_16x16x32_bf16 v[148:151], v[156:159], v[194:197], v[148:151]
	v_mfma_f32_16x16x32_bf16 v[140:143], v[170:173], v[194:197], v[140:143]
	v_mfma_f32_16x16x32_bf16 v[132:135], v[156:159], v[202:205], v[132:135]
	v_mfma_f32_16x16x32_bf16 v[124:127], v[170:173], v[202:205], v[124:127]
	v_mfma_f32_16x16x32_bf16 v[116:119], v[156:159], v[224:227], v[116:119]
	v_mfma_f32_16x16x32_bf16 v[108:111], v[170:173], v[224:227], v[108:111]
	s_waitcnt lgkmcnt(0)
	v_mfma_f32_16x16x32_bf16 v[76:79], v[156:159], v[240:243], v[76:79]
	v_mfma_f32_16x16x32_bf16 v[68:71], v[170:173], v[240:243], v[68:71]
	v_mfma_f32_16x16x32_bf16 v[144:147], v[174:177], v[190:193], 0
	v_mfma_f32_16x16x32_bf16 v[136:139], v[182:185], v[190:193], 0
	v_mfma_f32_16x16x32_bf16 v[128:131], v[174:177], v[198:201], 0
	v_mfma_f32_16x16x32_bf16 v[120:123], v[182:185], v[198:201], 0
	v_mfma_f32_16x16x32_bf16 v[112:115], v[174:177], v[220:223], 0
	v_mfma_f32_16x16x32_bf16 v[104:107], v[182:185], v[220:223], 0
	v_mfma_f32_16x16x32_bf16 v[72:75], v[174:177], v[228:231], 0
	v_mfma_f32_16x16x32_bf16 v[64:67], v[182:185], v[228:231], 0
	v_mfma_f32_16x16x32_bf16 v[144:147], v[178:181], v[194:197], v[144:147]
	v_mfma_f32_16x16x32_bf16 v[136:139], v[186:189], v[194:197], v[136:139]
	v_mfma_f32_16x16x32_bf16 v[128:131], v[178:181], v[202:205], v[128:131]
	v_mfma_f32_16x16x32_bf16 v[120:123], v[186:189], v[202:205], v[120:123]
	v_mfma_f32_16x16x32_bf16 v[112:115], v[178:181], v[224:227], v[112:115]
	v_mfma_f32_16x16x32_bf16 v[104:107], v[186:189], v[224:227], v[104:107]
	v_mfma_f32_16x16x32_bf16 v[72:75], v[178:181], v[240:243], v[72:75]
	v_mfma_f32_16x16x32_bf16 v[64:67], v[186:189], v[240:243], v[64:67]
	s_barrier
	ds_read_b128 v[190:193], v169 offset:16384
	ds_read_b128 v[194:197], v169 offset:17408
	ds_read_b128 v[198:201], v169 offset:18432
	ds_read_b128 v[202:205], v169 offset:19456
	ds_read_b128 v[220:223], v169 offset:20480
	ds_read_b128 v[224:227], v169 offset:21504
	ds_read_b128 v[228:231], v169 offset:22528
	ds_read_b128 v[240:243], v169 offset:23552
	s_mov_b32 m0, s7
	s_nop 0
	buffer_load_dwordx4 v166, s[28:31], s55 offen lds
	s_add_i32 s57, s55, 0x80000
	s_mov_b32 m0, s8
	s_nop 0
	buffer_load_dwordx4 v167, s[28:31], s55 offen lds
	s_nop 3
	s_mov_b32 m0, s9
	s_nop 0
	buffer_load_dwordx4 v166, s[28:31], s57 offen lds
	s_nop 3
	s_mov_b32 m0, s10
	s_nop 0
	buffer_load_dwordx4 v167, s[28:31], s57 offen lds
	s_nop 3
	s_mov_b32 m0, s6
	s_nop 0
	buffer_load_dwordx4 v166, s[24:27], s56 offen lds
	s_nop 3
	s_mov_b32 m0, s11
	s_nop 0
	buffer_load_dwordx4 v167, s[24:27], s56 offen lds
	s_waitcnt vmcnt(24)
	s_waitcnt lgkmcnt(0)
	s_barrier
	s_waitcnt lgkmcnt(7)
	v_mfma_f32_16x16x32_bf16 v[60:63], v[152:155], v[190:193], 0
	v_mfma_f32_16x16x32_bf16 v[52:55], v[160:163], v[190:193], 0
	s_waitcnt lgkmcnt(5)
	v_mfma_f32_16x16x32_bf16 v[44:47], v[152:155], v[198:201], 0
	v_mfma_f32_16x16x32_bf16 v[36:39], v[160:163], v[198:201], 0
	s_waitcnt lgkmcnt(3)
	v_mfma_f32_16x16x32_bf16 v[28:31], v[152:155], v[220:223], 0
	v_mfma_f32_16x16x32_bf16 v[20:23], v[160:163], v[220:223], 0
	s_waitcnt lgkmcnt(1)
	v_mfma_f32_16x16x32_bf16 v[12:15], v[152:155], v[228:231], 0
	v_mfma_f32_16x16x32_bf16 v[4:7], v[160:163], v[228:231], 0
	v_mfma_f32_16x16x32_bf16 v[60:63], v[156:159], v[194:197], v[60:63]
	v_mfma_f32_16x16x32_bf16 v[52:55], v[170:173], v[194:197], v[52:55]
	v_mfma_f32_16x16x32_bf16 v[44:47], v[156:159], v[202:205], v[44:47]
	v_mfma_f32_16x16x32_bf16 v[36:39], v[170:173], v[202:205], v[36:39]
	v_mfma_f32_16x16x32_bf16 v[28:31], v[156:159], v[224:227], v[28:31]
	v_mfma_f32_16x16x32_bf16 v[20:23], v[170:173], v[224:227], v[20:23]
	s_waitcnt lgkmcnt(0)
	v_mfma_f32_16x16x32_bf16 v[12:15], v[156:159], v[240:243], v[12:15]
	v_mfma_f32_16x16x32_bf16 v[4:7], v[170:173], v[240:243], v[4:7]
	v_mfma_f32_16x16x32_bf16 v[56:59], v[174:177], v[190:193], 0
	v_mfma_f32_16x16x32_bf16 v[48:51], v[182:185], v[190:193], 0
	v_mfma_f32_16x16x32_bf16 v[40:43], v[174:177], v[198:201], 0
	v_mfma_f32_16x16x32_bf16 v[32:35], v[182:185], v[198:201], 0
	v_mfma_f32_16x16x32_bf16 v[24:27], v[174:177], v[220:223], 0
	v_mfma_f32_16x16x32_bf16 v[16:19], v[182:185], v[220:223], 0
	v_mfma_f32_16x16x32_bf16 v[8:11], v[174:177], v[228:231], 0
	v_mfma_f32_16x16x32_bf16 v[0:3], v[182:185], v[228:231], 0
	v_mfma_f32_16x16x32_bf16 v[56:59], v[178:181], v[194:197], v[56:59]
	v_mfma_f32_16x16x32_bf16 v[48:51], v[186:189], v[194:197], v[48:51]
	v_mfma_f32_16x16x32_bf16 v[40:43], v[178:181], v[202:205], v[40:43]
	v_mfma_f32_16x16x32_bf16 v[32:35], v[186:189], v[202:205], v[32:35]
	v_mfma_f32_16x16x32_bf16 v[24:27], v[178:181], v[224:227], v[24:27]
	v_mfma_f32_16x16x32_bf16 v[16:19], v[186:189], v[224:227], v[16:19]
	v_mfma_f32_16x16x32_bf16 v[8:11], v[178:181], v[240:243], v[8:11]
	v_mfma_f32_16x16x32_bf16 v[0:3], v[186:189], v[240:243], v[0:3]
	s_barrier
	v_add_u32_e32 v164, 0x18000, v168
	ds_read_b128 v[152:155], v164
	ds_read_b128 v[156:159], v164 offset:1024
	ds_read_b128 v[160:163], v164 offset:2048
	ds_read_b128 v[170:173], v164 offset:3072
	v_add_u32_e32 v164, 0x1c000, v168
	ds_read_b128 v[174:177], v164
	ds_read_b128 v[178:181], v164 offset:1024
	ds_read_b128 v[182:185], v164 offset:2048
	ds_read_b128 v[186:189], v164 offset:3072
	ds_read_b128 v[190:193], v169 offset:32768
	ds_read_b128 v[194:197], v169 offset:33792
	ds_read_b128 v[198:201], v169 offset:34816
	ds_read_b128 v[202:205], v169 offset:35840
	ds_read_b128 v[220:223], v169 offset:36864
	ds_read_b128 v[224:227], v169 offset:37888
	ds_read_b128 v[228:231], v169 offset:38912
	ds_read_b128 v[240:243], v169 offset:39936
	s_add_i32 s56, s56, 0x80000
	s_mov_b32 m0, s12
	s_nop 0
	buffer_load_dwordx4 v166, s[24:27], s56 offen lds
	s_nop 3
	s_mov_b32 m0, s13
	s_nop 0
	buffer_load_dwordx4 v167, s[24:27], s56 offen lds
	s_waitcnt vmcnt(8)
	s_waitcnt lgkmcnt(0)
	s_barrier
	s_waitcnt lgkmcnt(7)
	v_mfma_f32_16x16x32_bf16 v[148:151], v[152:155], v[190:193], v[148:151]
	v_mfma_f32_16x16x32_bf16 v[140:143], v[160:163], v[190:193], v[140:143]
	s_waitcnt lgkmcnt(5)
	v_mfma_f32_16x16x32_bf16 v[132:135], v[152:155], v[198:201], v[132:135]
	v_mfma_f32_16x16x32_bf16 v[124:127], v[160:163], v[198:201], v[124:127]
	s_waitcnt lgkmcnt(3)
	v_mfma_f32_16x16x32_bf16 v[116:119], v[152:155], v[220:223], v[116:119]
	v_mfma_f32_16x16x32_bf16 v[108:111], v[160:163], v[220:223], v[108:111]
	s_waitcnt lgkmcnt(1)
	v_mfma_f32_16x16x32_bf16 v[76:79], v[152:155], v[228:231], v[76:79]
	v_mfma_f32_16x16x32_bf16 v[68:71], v[160:163], v[228:231], v[68:71]
	v_mfma_f32_16x16x32_bf16 v[148:151], v[156:159], v[194:197], v[148:151]
	v_mfma_f32_16x16x32_bf16 v[140:143], v[170:173], v[194:197], v[140:143]
	v_mfma_f32_16x16x32_bf16 v[132:135], v[156:159], v[202:205], v[132:135]
	v_mfma_f32_16x16x32_bf16 v[124:127], v[170:173], v[202:205], v[124:127]
	v_mfma_f32_16x16x32_bf16 v[116:119], v[156:159], v[224:227], v[116:119]
	v_mfma_f32_16x16x32_bf16 v[108:111], v[170:173], v[224:227], v[108:111]
	s_waitcnt lgkmcnt(0)
	v_mfma_f32_16x16x32_bf16 v[76:79], v[156:159], v[240:243], v[76:79]
	v_mfma_f32_16x16x32_bf16 v[68:71], v[170:173], v[240:243], v[68:71]
	v_mfma_f32_16x16x32_bf16 v[144:147], v[174:177], v[190:193], v[144:147]
	v_mfma_f32_16x16x32_bf16 v[136:139], v[182:185], v[190:193], v[136:139]
	v_mfma_f32_16x16x32_bf16 v[128:131], v[174:177], v[198:201], v[128:131]
	v_mfma_f32_16x16x32_bf16 v[120:123], v[182:185], v[198:201], v[120:123]
	v_mfma_f32_16x16x32_bf16 v[112:115], v[174:177], v[220:223], v[112:115]
	v_mfma_f32_16x16x32_bf16 v[104:107], v[182:185], v[220:223], v[104:107]
	v_mfma_f32_16x16x32_bf16 v[72:75], v[174:177], v[228:231], v[72:75]
	v_mfma_f32_16x16x32_bf16 v[64:67], v[182:185], v[228:231], v[64:67]
	v_mfma_f32_16x16x32_bf16 v[144:147], v[178:181], v[194:197], v[144:147]
	v_mfma_f32_16x16x32_bf16 v[136:139], v[186:189], v[194:197], v[136:139]
	v_mfma_f32_16x16x32_bf16 v[128:131], v[178:181], v[202:205], v[128:131]
	v_mfma_f32_16x16x32_bf16 v[120:123], v[186:189], v[202:205], v[120:123]
	v_mfma_f32_16x16x32_bf16 v[112:115], v[178:181], v[224:227], v[112:115]
	v_mfma_f32_16x16x32_bf16 v[104:107], v[186:189], v[224:227], v[104:107]
	v_mfma_f32_16x16x32_bf16 v[72:75], v[178:181], v[240:243], v[72:75]
	v_mfma_f32_16x16x32_bf16 v[64:67], v[186:189], v[240:243], v[64:67]
	s_barrier
	ds_read_b128 v[190:193], v169 offset:49152
	ds_read_b128 v[194:197], v169 offset:50176
	ds_read_b128 v[198:201], v169 offset:51200
	ds_read_b128 v[202:205], v169 offset:52224
	ds_read_b128 v[220:223], v169 offset:53248
	ds_read_b128 v[224:227], v169 offset:54272
	ds_read_b128 v[228:231], v169 offset:55296
	ds_read_b128 v[240:243], v169 offset:56320
	s_or_b32 s56, s55, 0x4000
	s_mov_b32 m0, s16
	s_nop 0
	buffer_load_dwordx4 v166, s[28:31], s56 offen lds
	s_add_i32 s55, s55, 0x84000
	s_mov_b32 m0, s17
	s_nop 0
	buffer_load_dwordx4 v167, s[28:31], s56 offen lds
	s_nop 3
	s_mov_b32 m0, s34
	s_nop 0
	buffer_load_dwordx4 v166, s[28:31], s55 offen lds
	s_nop 3
	s_mov_b32 m0, s40
	s_nop 0
	buffer_load_dwordx4 v167, s[28:31], s55 offen lds
	s_nop 3
	s_mov_b32 m0, s18
	s_nop 0
	buffer_load_dwordx4 v166, s[24:27], s53 offen lds
	s_nop 3
	s_mov_b32 m0, s19
	s_nop 0
	buffer_load_dwordx4 v167, s[24:27], s53 offen lds
	s_waitcnt vmcnt(8)
	s_waitcnt lgkmcnt(0)
	s_barrier
	s_waitcnt lgkmcnt(7)
	v_mfma_f32_16x16x32_bf16 v[60:63], v[152:155], v[190:193], v[60:63]
	v_mfma_f32_16x16x32_bf16 v[52:55], v[160:163], v[190:193], v[52:55]
	s_waitcnt lgkmcnt(5)
	v_mfma_f32_16x16x32_bf16 v[44:47], v[152:155], v[198:201], v[44:47]
	v_mfma_f32_16x16x32_bf16 v[36:39], v[160:163], v[198:201], v[36:39]
	s_waitcnt lgkmcnt(3)
	v_mfma_f32_16x16x32_bf16 v[28:31], v[152:155], v[220:223], v[28:31]
	v_mfma_f32_16x16x32_bf16 v[20:23], v[160:163], v[220:223], v[20:23]
	s_waitcnt lgkmcnt(1)
	v_mfma_f32_16x16x32_bf16 v[12:15], v[152:155], v[228:231], v[12:15]
	v_mfma_f32_16x16x32_bf16 v[4:7], v[160:163], v[228:231], v[4:7]
	v_mfma_f32_16x16x32_bf16 v[60:63], v[156:159], v[194:197], v[60:63]
	v_mfma_f32_16x16x32_bf16 v[52:55], v[170:173], v[194:197], v[52:55]
	v_mfma_f32_16x16x32_bf16 v[44:47], v[156:159], v[202:205], v[44:47]
	v_mfma_f32_16x16x32_bf16 v[36:39], v[170:173], v[202:205], v[36:39]
	v_mfma_f32_16x16x32_bf16 v[28:31], v[156:159], v[224:227], v[28:31]
	v_mfma_f32_16x16x32_bf16 v[20:23], v[170:173], v[224:227], v[20:23]
	s_waitcnt lgkmcnt(0)
	v_mfma_f32_16x16x32_bf16 v[12:15], v[156:159], v[240:243], v[12:15]
	v_mfma_f32_16x16x32_bf16 v[4:7], v[170:173], v[240:243], v[4:7]
	v_mfma_f32_16x16x32_bf16 v[56:59], v[174:177], v[190:193], v[56:59]
	v_mfma_f32_16x16x32_bf16 v[48:51], v[182:185], v[190:193], v[48:51]
	v_mfma_f32_16x16x32_bf16 v[40:43], v[174:177], v[198:201], v[40:43]
	v_mfma_f32_16x16x32_bf16 v[32:35], v[182:185], v[198:201], v[32:35]
	v_mfma_f32_16x16x32_bf16 v[24:27], v[174:177], v[220:223], v[24:27]
	v_mfma_f32_16x16x32_bf16 v[16:19], v[182:185], v[220:223], v[16:19]
	v_mfma_f32_16x16x32_bf16 v[8:11], v[174:177], v[228:231], v[8:11]
	v_mfma_f32_16x16x32_bf16 v[0:3], v[182:185], v[228:231], v[0:3]
	v_mfma_f32_16x16x32_bf16 v[56:59], v[178:181], v[194:197], v[56:59]
	v_mfma_f32_16x16x32_bf16 v[48:51], v[186:189], v[194:197], v[48:51]
	v_mfma_f32_16x16x32_bf16 v[40:43], v[178:181], v[202:205], v[40:43]
	v_mfma_f32_16x16x32_bf16 v[32:35], v[186:189], v[202:205], v[32:35]
	v_mfma_f32_16x16x32_bf16 v[24:27], v[178:181], v[224:227], v[24:27]
	v_mfma_f32_16x16x32_bf16 v[16:19], v[186:189], v[224:227], v[16:19]
	v_mfma_f32_16x16x32_bf16 v[8:11], v[178:181], v[240:243], v[8:11]
	v_mfma_f32_16x16x32_bf16 v[0:3], v[186:189], v[240:243], v[0:3]
	s_barrier
	s_add_i32 s52, s52, 2
	s_add_i32 s37, s37, 0x8000
	s_add_i32 s51, s51, 0x8000
.LBB0_795:
	v_add_u32_e32 v164, 0x10000, v168
	ds_read_b128 v[152:155], v164
	ds_read_b128 v[156:159], v164 offset:1024
	ds_read_b128 v[160:163], v164 offset:2048
	ds_read_b128 v[170:173], v164 offset:3072
	v_add_u32_e32 v164, 0x14000, v168
	ds_read_b128 v[174:177], v164
	ds_read_b128 v[178:181], v164 offset:1024
	ds_read_b128 v[182:185], v164 offset:2048
	ds_read_b128 v[186:189], v164 offset:3072
	s_add_i32 s53, s37, 0xfff84000
	s_cmp_eq_u32 s52, 28
	s_cselect_b32 s56, s4, s53
	s_cselect_b32 s55, s5, s51
	s_or_b32 s53, s56, 0x4000
	ds_read_b128 v[190:193], v169
	ds_read_b128 v[194:197], v169 offset:1024
	ds_read_b128 v[198:201], v169 offset:2048
	ds_read_b128 v[202:205], v169 offset:3072
	ds_read_b128 v[220:223], v169 offset:4096
	ds_read_b128 v[224:227], v169 offset:5120
	ds_read_b128 v[228:231], v169 offset:6144
	ds_read_b128 v[240:243], v169 offset:7168
	s_mov_b32 m0, s41
	s_nop 0
	buffer_load_dwordx4 v166, s[24:27], s37 offen lds
	s_nop 3
	s_mov_b32 m0, s42
	s_nop 0
	buffer_load_dwordx4 v167, s[24:27], s37 offen lds
	s_waitcnt vmcnt(8)
	s_waitcnt lgkmcnt(0)
	s_barrier
	s_waitcnt lgkmcnt(7)
	v_mfma_f32_16x16x32_bf16 v[148:151], v[152:155], v[190:193], v[148:151]
	v_mfma_f32_16x16x32_bf16 v[140:143], v[160:163], v[190:193], v[140:143]
	s_waitcnt lgkmcnt(5)
	v_mfma_f32_16x16x32_bf16 v[132:135], v[152:155], v[198:201], v[132:135]
	v_mfma_f32_16x16x32_bf16 v[124:127], v[160:163], v[198:201], v[124:127]
	s_waitcnt lgkmcnt(3)
	v_mfma_f32_16x16x32_bf16 v[116:119], v[152:155], v[220:223], v[116:119]
	v_mfma_f32_16x16x32_bf16 v[108:111], v[160:163], v[220:223], v[108:111]
	s_waitcnt lgkmcnt(1)
	v_mfma_f32_16x16x32_bf16 v[76:79], v[152:155], v[228:231], v[76:79]
	v_mfma_f32_16x16x32_bf16 v[68:71], v[160:163], v[228:231], v[68:71]
	v_mfma_f32_16x16x32_bf16 v[148:151], v[156:159], v[194:197], v[148:151]
	v_mfma_f32_16x16x32_bf16 v[140:143], v[170:173], v[194:197], v[140:143]
	v_mfma_f32_16x16x32_bf16 v[132:135], v[156:159], v[202:205], v[132:135]
	v_mfma_f32_16x16x32_bf16 v[124:127], v[170:173], v[202:205], v[124:127]
	v_mfma_f32_16x16x32_bf16 v[116:119], v[156:159], v[224:227], v[116:119]
	v_mfma_f32_16x16x32_bf16 v[108:111], v[170:173], v[224:227], v[108:111]
	s_waitcnt lgkmcnt(0)
	v_mfma_f32_16x16x32_bf16 v[76:79], v[156:159], v[240:243], v[76:79]
	v_mfma_f32_16x16x32_bf16 v[68:71], v[170:173], v[240:243], v[68:71]
	v_mfma_f32_16x16x32_bf16 v[144:147], v[174:177], v[190:193], v[144:147]
	v_mfma_f32_16x16x32_bf16 v[136:139], v[182:185], v[190:193], v[136:139]
	v_mfma_f32_16x16x32_bf16 v[128:131], v[174:177], v[198:201], v[128:131]
	v_mfma_f32_16x16x32_bf16 v[120:123], v[182:185], v[198:201], v[120:123]
	v_mfma_f32_16x16x32_bf16 v[112:115], v[174:177], v[220:223], v[112:115]
	v_mfma_f32_16x16x32_bf16 v[104:107], v[182:185], v[220:223], v[104:107]
	v_mfma_f32_16x16x32_bf16 v[72:75], v[174:177], v[228:231], v[72:75]
	v_mfma_f32_16x16x32_bf16 v[64:67], v[182:185], v[228:231], v[64:67]
	v_mfma_f32_16x16x32_bf16 v[144:147], v[178:181], v[194:197], v[144:147]
	v_mfma_f32_16x16x32_bf16 v[136:139], v[186:189], v[194:197], v[136:139]
	v_mfma_f32_16x16x32_bf16 v[128:131], v[178:181], v[202:205], v[128:131]
	v_mfma_f32_16x16x32_bf16 v[120:123], v[186:189], v[202:205], v[120:123]
	v_mfma_f32_16x16x32_bf16 v[112:115], v[178:181], v[224:227], v[112:115]
	v_mfma_f32_16x16x32_bf16 v[104:107], v[186:189], v[224:227], v[104:107]
	v_mfma_f32_16x16x32_bf16 v[72:75], v[178:181], v[240:243], v[72:75]
	v_mfma_f32_16x16x32_bf16 v[64:67], v[186:189], v[240:243], v[64:67]
	s_barrier
	ds_read_b128 v[190:193], v169 offset:16384
	ds_read_b128 v[194:197], v169 offset:17408
	ds_read_b128 v[198:201], v169 offset:18432
	ds_read_b128 v[202:205], v169 offset:19456
	ds_read_b128 v[220:223], v169 offset:20480
	ds_read_b128 v[224:227], v169 offset:21504
	ds_read_b128 v[228:231], v169 offset:22528
	ds_read_b128 v[240:243], v169 offset:23552
	s_mov_b32 m0, s7
	s_nop 0
	buffer_load_dwordx4 v166, s[28:31], s55 offen lds
	s_add_i32 s57, s55, 0x80000
	s_mov_b32 m0, s8
	s_nop 0
	buffer_load_dwordx4 v167, s[28:31], s55 offen lds
	s_nop 3
	s_mov_b32 m0, s9
	s_nop 0
	buffer_load_dwordx4 v166, s[28:31], s57 offen lds
	s_nop 3
	s_mov_b32 m0, s10
	s_nop 0
	buffer_load_dwordx4 v167, s[28:31], s57 offen lds
	s_nop 3
	s_mov_b32 m0, s6
	s_nop 0
	buffer_load_dwordx4 v166, s[24:27], s56 offen lds
	s_nop 3
	s_mov_b32 m0, s11
	s_nop 0
	buffer_load_dwordx4 v167, s[24:27], s56 offen lds
	s_waitcnt vmcnt(8)
	s_waitcnt lgkmcnt(0)
	s_barrier
	s_waitcnt lgkmcnt(7)
	v_mfma_f32_16x16x32_bf16 v[60:63], v[152:155], v[190:193], v[60:63]
	v_mfma_f32_16x16x32_bf16 v[52:55], v[160:163], v[190:193], v[52:55]
	s_waitcnt lgkmcnt(5)
	v_mfma_f32_16x16x32_bf16 v[44:47], v[152:155], v[198:201], v[44:47]
	v_mfma_f32_16x16x32_bf16 v[36:39], v[160:163], v[198:201], v[36:39]
	s_waitcnt lgkmcnt(3)
	v_mfma_f32_16x16x32_bf16 v[28:31], v[152:155], v[220:223], v[28:31]
	v_mfma_f32_16x16x32_bf16 v[20:23], v[160:163], v[220:223], v[20:23]
	s_waitcnt lgkmcnt(1)
	v_mfma_f32_16x16x32_bf16 v[12:15], v[152:155], v[228:231], v[12:15]
	v_mfma_f32_16x16x32_bf16 v[4:7], v[160:163], v[228:231], v[4:7]
	v_mfma_f32_16x16x32_bf16 v[60:63], v[156:159], v[194:197], v[60:63]
	v_mfma_f32_16x16x32_bf16 v[52:55], v[170:173], v[194:197], v[52:55]
	v_mfma_f32_16x16x32_bf16 v[44:47], v[156:159], v[202:205], v[44:47]
	v_mfma_f32_16x16x32_bf16 v[36:39], v[170:173], v[202:205], v[36:39]
	v_mfma_f32_16x16x32_bf16 v[28:31], v[156:159], v[224:227], v[28:31]
	v_mfma_f32_16x16x32_bf16 v[20:23], v[170:173], v[224:227], v[20:23]
	s_waitcnt lgkmcnt(0)
	v_mfma_f32_16x16x32_bf16 v[12:15], v[156:159], v[240:243], v[12:15]
	v_mfma_f32_16x16x32_bf16 v[4:7], v[170:173], v[240:243], v[4:7]
	v_mfma_f32_16x16x32_bf16 v[56:59], v[174:177], v[190:193], v[56:59]
	v_mfma_f32_16x16x32_bf16 v[48:51], v[182:185], v[190:193], v[48:51]
	v_mfma_f32_16x16x32_bf16 v[40:43], v[174:177], v[198:201], v[40:43]
	v_mfma_f32_16x16x32_bf16 v[32:35], v[182:185], v[198:201], v[32:35]
	v_mfma_f32_16x16x32_bf16 v[24:27], v[174:177], v[220:223], v[24:27]
	v_mfma_f32_16x16x32_bf16 v[16:19], v[182:185], v[220:223], v[16:19]
	v_mfma_f32_16x16x32_bf16 v[8:11], v[174:177], v[228:231], v[8:11]
	v_mfma_f32_16x16x32_bf16 v[0:3], v[182:185], v[228:231], v[0:3]
	v_mfma_f32_16x16x32_bf16 v[56:59], v[178:181], v[194:197], v[56:59]
	v_mfma_f32_16x16x32_bf16 v[48:51], v[186:189], v[194:197], v[48:51]
	v_mfma_f32_16x16x32_bf16 v[40:43], v[178:181], v[202:205], v[40:43]
	v_mfma_f32_16x16x32_bf16 v[32:35], v[186:189], v[202:205], v[32:35]
	v_mfma_f32_16x16x32_bf16 v[24:27], v[178:181], v[224:227], v[24:27]
	v_mfma_f32_16x16x32_bf16 v[16:19], v[186:189], v[224:227], v[16:19]
	v_mfma_f32_16x16x32_bf16 v[8:11], v[178:181], v[240:243], v[8:11]
	v_mfma_f32_16x16x32_bf16 v[0:3], v[186:189], v[240:243], v[0:3]
	s_barrier
	v_add_u32_e32 v164, 0x18000, v168
	ds_read_b128 v[152:155], v164
	ds_read_b128 v[156:159], v164 offset:1024
	ds_read_b128 v[160:163], v164 offset:2048
	ds_read_b128 v[170:173], v164 offset:3072
	v_add_u32_e32 v164, 0x1c000, v168
	ds_read_b128 v[174:177], v164
	ds_read_b128 v[178:181], v164 offset:1024
	ds_read_b128 v[182:185], v164 offset:2048
	ds_read_b128 v[186:189], v164 offset:3072
	ds_read_b128 v[190:193], v169 offset:32768
	ds_read_b128 v[194:197], v169 offset:33792
	ds_read_b128 v[198:201], v169 offset:34816
	ds_read_b128 v[202:205], v169 offset:35840
	ds_read_b128 v[220:223], v169 offset:36864
	ds_read_b128 v[224:227], v169 offset:37888
	ds_read_b128 v[228:231], v169 offset:38912
	ds_read_b128 v[240:243], v169 offset:39936
	s_add_i32 s56, s56, 0x80000
	s_mov_b32 m0, s12
	s_nop 0
	buffer_load_dwordx4 v166, s[24:27], s56 offen lds
	s_nop 3
	s_mov_b32 m0, s13
	s_nop 0
	buffer_load_dwordx4 v167, s[24:27], s56 offen lds
	s_waitcnt vmcnt(8)
	s_waitcnt lgkmcnt(0)
	s_barrier
	s_waitcnt lgkmcnt(7)
	v_mfma_f32_16x16x32_bf16 v[148:151], v[152:155], v[190:193], v[148:151]
	v_mfma_f32_16x16x32_bf16 v[140:143], v[160:163], v[190:193], v[140:143]
	s_waitcnt lgkmcnt(5)
	v_mfma_f32_16x16x32_bf16 v[132:135], v[152:155], v[198:201], v[132:135]
	v_mfma_f32_16x16x32_bf16 v[124:127], v[160:163], v[198:201], v[124:127]
	s_waitcnt lgkmcnt(3)
	v_mfma_f32_16x16x32_bf16 v[116:119], v[152:155], v[220:223], v[116:119]
	v_mfma_f32_16x16x32_bf16 v[108:111], v[160:163], v[220:223], v[108:111]
	s_waitcnt lgkmcnt(1)
	v_mfma_f32_16x16x32_bf16 v[76:79], v[152:155], v[228:231], v[76:79]
	v_mfma_f32_16x16x32_bf16 v[68:71], v[160:163], v[228:231], v[68:71]
	v_mfma_f32_16x16x32_bf16 v[148:151], v[156:159], v[194:197], v[148:151]
	v_mfma_f32_16x16x32_bf16 v[140:143], v[170:173], v[194:197], v[140:143]
	v_mfma_f32_16x16x32_bf16 v[132:135], v[156:159], v[202:205], v[132:135]
	v_mfma_f32_16x16x32_bf16 v[124:127], v[170:173], v[202:205], v[124:127]
	v_mfma_f32_16x16x32_bf16 v[116:119], v[156:159], v[224:227], v[116:119]
	v_mfma_f32_16x16x32_bf16 v[108:111], v[170:173], v[224:227], v[108:111]
	s_waitcnt lgkmcnt(0)
	v_mfma_f32_16x16x32_bf16 v[76:79], v[156:159], v[240:243], v[76:79]
	v_mfma_f32_16x16x32_bf16 v[68:71], v[170:173], v[240:243], v[68:71]
	v_mfma_f32_16x16x32_bf16 v[144:147], v[174:177], v[190:193], v[144:147]
	v_mfma_f32_16x16x32_bf16 v[136:139], v[182:185], v[190:193], v[136:139]
	v_mfma_f32_16x16x32_bf16 v[128:131], v[174:177], v[198:201], v[128:131]
	v_mfma_f32_16x16x32_bf16 v[120:123], v[182:185], v[198:201], v[120:123]
	v_mfma_f32_16x16x32_bf16 v[112:115], v[174:177], v[220:223], v[112:115]
	v_mfma_f32_16x16x32_bf16 v[104:107], v[182:185], v[220:223], v[104:107]
	v_mfma_f32_16x16x32_bf16 v[72:75], v[174:177], v[228:231], v[72:75]
	v_mfma_f32_16x16x32_bf16 v[64:67], v[182:185], v[228:231], v[64:67]
	v_mfma_f32_16x16x32_bf16 v[144:147], v[178:181], v[194:197], v[144:147]
	v_mfma_f32_16x16x32_bf16 v[136:139], v[186:189], v[194:197], v[136:139]
	v_mfma_f32_16x16x32_bf16 v[128:131], v[178:181], v[202:205], v[128:131]
	v_mfma_f32_16x16x32_bf16 v[120:123], v[186:189], v[202:205], v[120:123]
	v_mfma_f32_16x16x32_bf16 v[112:115], v[178:181], v[224:227], v[112:115]
	v_mfma_f32_16x16x32_bf16 v[104:107], v[186:189], v[224:227], v[104:107]
	v_mfma_f32_16x16x32_bf16 v[72:75], v[178:181], v[240:243], v[72:75]
	v_mfma_f32_16x16x32_bf16 v[64:67], v[186:189], v[240:243], v[64:67]
	s_barrier
	ds_read_b128 v[190:193], v169 offset:49152
	ds_read_b128 v[194:197], v169 offset:50176
	ds_read_b128 v[198:201], v169 offset:51200
	ds_read_b128 v[202:205], v169 offset:52224
	ds_read_b128 v[220:223], v169 offset:53248
	ds_read_b128 v[224:227], v169 offset:54272
	ds_read_b128 v[228:231], v169 offset:55296
	ds_read_b128 v[240:243], v169 offset:56320
	s_or_b32 s56, s55, 0x4000
	s_mov_b32 m0, s16
	s_nop 0
	buffer_load_dwordx4 v166, s[28:31], s56 offen lds
	s_add_i32 s55, s55, 0x84000
	s_mov_b32 m0, s17
	s_nop 0
	buffer_load_dwordx4 v167, s[28:31], s56 offen lds
	s_nop 3
	s_mov_b32 m0, s34
	s_nop 0
	buffer_load_dwordx4 v166, s[28:31], s55 offen lds
	s_nop 3
	s_mov_b32 m0, s40
	s_nop 0
	buffer_load_dwordx4 v167, s[28:31], s55 offen lds
	s_nop 3
	s_mov_b32 m0, s18
	s_nop 0
	buffer_load_dwordx4 v166, s[24:27], s53 offen lds
	s_nop 3
	s_mov_b32 m0, s19
	s_nop 0
	buffer_load_dwordx4 v167, s[24:27], s53 offen lds
	s_waitcnt vmcnt(8)
	s_waitcnt lgkmcnt(0)
	s_barrier
	s_waitcnt lgkmcnt(7)
	v_mfma_f32_16x16x32_bf16 v[60:63], v[152:155], v[190:193], v[60:63]
	v_mfma_f32_16x16x32_bf16 v[52:55], v[160:163], v[190:193], v[52:55]
	s_waitcnt lgkmcnt(5)
	v_mfma_f32_16x16x32_bf16 v[44:47], v[152:155], v[198:201], v[44:47]
	v_mfma_f32_16x16x32_bf16 v[36:39], v[160:163], v[198:201], v[36:39]
	s_waitcnt lgkmcnt(3)
	v_mfma_f32_16x16x32_bf16 v[28:31], v[152:155], v[220:223], v[28:31]
	v_mfma_f32_16x16x32_bf16 v[20:23], v[160:163], v[220:223], v[20:23]
	s_waitcnt lgkmcnt(1)
	v_mfma_f32_16x16x32_bf16 v[12:15], v[152:155], v[228:231], v[12:15]
	v_mfma_f32_16x16x32_bf16 v[4:7], v[160:163], v[228:231], v[4:7]
	v_mfma_f32_16x16x32_bf16 v[60:63], v[156:159], v[194:197], v[60:63]
	v_mfma_f32_16x16x32_bf16 v[52:55], v[170:173], v[194:197], v[52:55]
	v_mfma_f32_16x16x32_bf16 v[44:47], v[156:159], v[202:205], v[44:47]
	v_mfma_f32_16x16x32_bf16 v[36:39], v[170:173], v[202:205], v[36:39]
	v_mfma_f32_16x16x32_bf16 v[28:31], v[156:159], v[224:227], v[28:31]
	v_mfma_f32_16x16x32_bf16 v[20:23], v[170:173], v[224:227], v[20:23]
	s_waitcnt lgkmcnt(0)
	v_mfma_f32_16x16x32_bf16 v[12:15], v[156:159], v[240:243], v[12:15]
	v_mfma_f32_16x16x32_bf16 v[4:7], v[170:173], v[240:243], v[4:7]
	v_mfma_f32_16x16x32_bf16 v[56:59], v[174:177], v[190:193], v[56:59]
	v_mfma_f32_16x16x32_bf16 v[48:51], v[182:185], v[190:193], v[48:51]
	v_mfma_f32_16x16x32_bf16 v[40:43], v[174:177], v[198:201], v[40:43]
	v_mfma_f32_16x16x32_bf16 v[32:35], v[182:185], v[198:201], v[32:35]
	v_mfma_f32_16x16x32_bf16 v[24:27], v[174:177], v[220:223], v[24:27]
	v_mfma_f32_16x16x32_bf16 v[16:19], v[182:185], v[220:223], v[16:19]
	v_mfma_f32_16x16x32_bf16 v[8:11], v[174:177], v[228:231], v[8:11]
	v_mfma_f32_16x16x32_bf16 v[0:3], v[182:185], v[228:231], v[0:3]
	v_mfma_f32_16x16x32_bf16 v[56:59], v[178:181], v[194:197], v[56:59]
	v_mfma_f32_16x16x32_bf16 v[48:51], v[186:189], v[194:197], v[48:51]
	v_mfma_f32_16x16x32_bf16 v[40:43], v[178:181], v[202:205], v[40:43]
	v_mfma_f32_16x16x32_bf16 v[32:35], v[186:189], v[202:205], v[32:35]
	v_mfma_f32_16x16x32_bf16 v[24:27], v[178:181], v[224:227], v[24:27]
	v_mfma_f32_16x16x32_bf16 v[16:19], v[186:189], v[224:227], v[16:19]
	v_mfma_f32_16x16x32_bf16 v[8:11], v[178:181], v[240:243], v[8:11]
	v_mfma_f32_16x16x32_bf16 v[0:3], v[186:189], v[240:243], v[0:3]
	s_barrier
	s_add_i32 s52, s52, 2
	s_add_i32 s37, s37, 0x8000
	s_add_i32 s51, s51, 0x8000
	s_cmp_gt_u32 s52, 29
	s_cbranch_scc0 .LBB0_795

.Lnb_p6:
	s_add_i32 s11, s8, 0xffea4000
	s_cmpk_eq_i32 s10, 0x54
	s_cselect_b32 s13, s6, s11
	s_cselect_b32 s12, s7, s9
	s_or_b32 s11, s13, 0x4000
	s_mov_b32 m0, s87
	s_nop 0
	buffer_load_dwordx4 v220, s[20:23], s8 offen lds
	s_nop 3
	s_mov_b32 m0, s89
	s_nop 0
	buffer_load_dwordx4 v221, s[20:23], s8 offen lds
	s_waitcnt vmcnt(24)
	s_waitcnt lgkmcnt(0)
	s_barrier
	s_waitcnt lgkmcnt(7)
	v_mfma_f32_16x16x32_bf16 v[164:167], v[128:131], v[184:187], 0
	v_mfma_f32_16x16x32_bf16 v[160:163], v[152:155], v[184:187], 0
	s_waitcnt lgkmcnt(5)
	v_mfma_f32_16x16x32_bf16 v[136:139], v[128:131], v[192:195], 0
	v_mfma_f32_16x16x32_bf16 v[132:135], v[152:155], v[192:195], 0
	s_waitcnt lgkmcnt(3)
	v_mfma_f32_16x16x32_bf16 v[116:119], v[128:131], v[200:203], 0
	v_mfma_f32_16x16x32_bf16 v[112:115], v[152:155], v[200:203], 0
	s_waitcnt lgkmcnt(1)
	v_mfma_f32_16x16x32_bf16 v[76:79], v[128:131], v[224:227], 0
	v_mfma_f32_16x16x32_bf16 v[72:75], v[152:155], v[224:227], 0
	v_mfma_f32_16x16x32_bf16 v[164:167], v[140:143], v[188:191], v[164:167]
	v_mfma_f32_16x16x32_bf16 v[160:163], v[156:159], v[188:191], v[160:163]
	v_mfma_f32_16x16x32_bf16 v[136:139], v[140:143], v[196:199], v[136:139]
	v_mfma_f32_16x16x32_bf16 v[132:135], v[156:159], v[196:199], v[132:135]
	v_mfma_f32_16x16x32_bf16 v[116:119], v[140:143], v[204:207], v[116:119]
	v_mfma_f32_16x16x32_bf16 v[112:115], v[156:159], v[204:207], v[112:115]
	s_waitcnt lgkmcnt(0)
	v_mfma_f32_16x16x32_bf16 v[76:79], v[140:143], v[228:231], v[76:79]
	v_mfma_f32_16x16x32_bf16 v[72:75], v[156:159], v[228:231], v[72:75]
	v_mfma_f32_16x16x32_bf16 v[148:151], v[168:171], v[184:187], 0
	v_mfma_f32_16x16x32_bf16 v[144:147], v[176:179], v[184:187], 0
	v_mfma_f32_16x16x32_bf16 v[124:127], v[168:171], v[192:195], 0
	v_mfma_f32_16x16x32_bf16 v[120:123], v[176:179], v[192:195], 0
	v_mfma_f32_16x16x32_bf16 v[108:111], v[168:171], v[200:203], 0
	v_mfma_f32_16x16x32_bf16 v[104:107], v[176:179], v[200:203], 0
	v_mfma_f32_16x16x32_bf16 v[68:71], v[168:171], v[224:227], 0
	v_mfma_f32_16x16x32_bf16 v[64:67], v[176:179], v[224:227], 0
	v_mfma_f32_16x16x32_bf16 v[148:151], v[172:175], v[188:191], v[148:151]
	v_mfma_f32_16x16x32_bf16 v[144:147], v[180:183], v[188:191], v[144:147]
	v_mfma_f32_16x16x32_bf16 v[124:127], v[172:175], v[196:199], v[124:127]
	v_mfma_f32_16x16x32_bf16 v[120:123], v[180:183], v[196:199], v[120:123]
	v_mfma_f32_16x16x32_bf16 v[108:111], v[172:175], v[204:207], v[108:111]
	v_mfma_f32_16x16x32_bf16 v[104:107], v[180:183], v[204:207], v[104:107]
	v_mfma_f32_16x16x32_bf16 v[68:71], v[172:175], v[228:231], v[68:71]
	v_mfma_f32_16x16x32_bf16 v[64:67], v[180:183], v[228:231], v[64:67]
	s_barrier
	ds_read_b128 v[184:187], v223 offset:16384
	ds_read_b128 v[188:191], v223 offset:17408
	ds_read_b128 v[192:195], v223 offset:18432
	ds_read_b128 v[196:199], v223 offset:19456
	ds_read_b128 v[200:203], v223 offset:20480
	ds_read_b128 v[204:207], v223 offset:21504
	ds_read_b128 v[224:227], v223 offset:22528
	ds_read_b128 v[228:231], v223 offset:23552
	s_mov_b32 m0, s51
	s_nop 0
	buffer_load_dwordx4 v220, s[52:55], s12 offen lds
	s_add_i32 s14, s12, 0x160000
	s_mov_b32 m0, s74
	s_nop 0
	buffer_load_dwordx4 v221, s[52:55], s12 offen lds
	s_nop 3
	s_mov_b32 m0, s75
	s_nop 0
	buffer_load_dwordx4 v220, s[52:55], s14 offen lds
	s_nop 3
	s_mov_b32 m0, s76
	s_nop 0
	buffer_load_dwordx4 v221, s[52:55], s14 offen lds
	s_nop 3
	s_mov_b32 m0, s31
	s_nop 0
	buffer_load_dwordx4 v220, s[20:23], s13 offen lds
	s_nop 3
	s_mov_b32 m0, s77
	s_nop 0
	buffer_load_dwordx4 v221, s[20:23], s13 offen lds
	s_waitcnt vmcnt(24)
	s_waitcnt lgkmcnt(0)
	s_barrier
	s_waitcnt lgkmcnt(7)
	v_mfma_f32_16x16x32_bf16 v[60:63], v[128:131], v[184:187], 0
	v_mfma_f32_16x16x32_bf16 v[56:59], v[152:155], v[184:187], 0
	s_waitcnt lgkmcnt(5)
	v_mfma_f32_16x16x32_bf16 v[44:47], v[128:131], v[192:195], 0
	v_mfma_f32_16x16x32_bf16 v[40:43], v[152:155], v[192:195], 0
	s_waitcnt lgkmcnt(3)
	v_mfma_f32_16x16x32_bf16 v[28:31], v[128:131], v[200:203], 0
	v_mfma_f32_16x16x32_bf16 v[24:27], v[152:155], v[200:203], 0
	s_waitcnt lgkmcnt(1)
	v_mfma_f32_16x16x32_bf16 v[12:15], v[128:131], v[224:227], 0
	v_mfma_f32_16x16x32_bf16 v[8:11], v[152:155], v[224:227], 0
	v_mfma_f32_16x16x32_bf16 v[60:63], v[140:143], v[188:191], v[60:63]
	v_mfma_f32_16x16x32_bf16 v[56:59], v[156:159], v[188:191], v[56:59]
	v_mfma_f32_16x16x32_bf16 v[44:47], v[140:143], v[196:199], v[44:47]
	v_mfma_f32_16x16x32_bf16 v[40:43], v[156:159], v[196:199], v[40:43]
	v_mfma_f32_16x16x32_bf16 v[28:31], v[140:143], v[204:207], v[28:31]
	v_mfma_f32_16x16x32_bf16 v[24:27], v[156:159], v[204:207], v[24:27]
	s_waitcnt lgkmcnt(0)
	v_mfma_f32_16x16x32_bf16 v[12:15], v[140:143], v[228:231], v[12:15]
	v_mfma_f32_16x16x32_bf16 v[8:11], v[156:159], v[228:231], v[8:11]
	v_mfma_f32_16x16x32_bf16 v[52:55], v[168:171], v[184:187], 0
	v_mfma_f32_16x16x32_bf16 v[48:51], v[176:179], v[184:187], 0
	v_mfma_f32_16x16x32_bf16 v[36:39], v[168:171], v[192:195], 0
	v_mfma_f32_16x16x32_bf16 v[32:35], v[176:179], v[192:195], 0
	v_mfma_f32_16x16x32_bf16 v[20:23], v[168:171], v[200:203], 0
	v_mfma_f32_16x16x32_bf16 v[16:19], v[176:179], v[200:203], 0
	v_mfma_f32_16x16x32_bf16 v[4:7], v[168:171], v[224:227], 0
	v_mfma_f32_16x16x32_bf16 v[0:3], v[176:179], v[224:227], 0
	v_mfma_f32_16x16x32_bf16 v[52:55], v[172:175], v[188:191], v[52:55]
	v_mfma_f32_16x16x32_bf16 v[48:51], v[180:183], v[188:191], v[48:51]
	v_mfma_f32_16x16x32_bf16 v[36:39], v[172:175], v[196:199], v[36:39]
	v_mfma_f32_16x16x32_bf16 v[32:35], v[180:183], v[196:199], v[32:35]
	v_mfma_f32_16x16x32_bf16 v[20:23], v[172:175], v[204:207], v[20:23]
	v_mfma_f32_16x16x32_bf16 v[16:19], v[180:183], v[204:207], v[16:19]
	v_mfma_f32_16x16x32_bf16 v[4:7], v[172:175], v[228:231], v[4:7]
	v_mfma_f32_16x16x32_bf16 v[0:3], v[180:183], v[228:231], v[0:3]
	s_barrier
	v_add_u32_e32 v156, 0x18000, v222
	v_add_u32_e32 v180, 0x1c000, v222
	ds_read_b128 v[128:131], v156
	ds_read_b128 v[140:143], v156 offset:1024
	ds_read_b128 v[152:155], v156 offset:2048
	ds_read_b128 v[156:159], v156 offset:3072
	ds_read_b128 v[168:171], v180
	ds_read_b128 v[172:175], v180 offset:1024
	ds_read_b128 v[176:179], v180 offset:2048
	ds_read_b128 v[180:183], v180 offset:3072
	ds_read_b128 v[184:187], v223 offset:32768
	ds_read_b128 v[188:191], v223 offset:33792
	ds_read_b128 v[192:195], v223 offset:34816
	ds_read_b128 v[196:199], v223 offset:35840
	ds_read_b128 v[200:203], v223 offset:36864
	ds_read_b128 v[204:207], v223 offset:37888
	ds_read_b128 v[224:227], v223 offset:38912
	ds_read_b128 v[228:231], v223 offset:39936
	s_add_i32 s13, s13, 0x160000
	s_mov_b32 m0, s78
	s_nop 0
	buffer_load_dwordx4 v220, s[20:23], s13 offen lds
	s_nop 3
	s_mov_b32 m0, s79
	s_nop 0
	buffer_load_dwordx4 v221, s[20:23], s13 offen lds
	s_waitcnt vmcnt(8)
	s_waitcnt lgkmcnt(0)
	s_barrier
	s_waitcnt lgkmcnt(7)
	v_mfma_f32_16x16x32_bf16 v[164:167], v[128:131], v[184:187], v[164:167]
	v_mfma_f32_16x16x32_bf16 v[160:163], v[152:155], v[184:187], v[160:163]
	s_waitcnt lgkmcnt(5)
	v_mfma_f32_16x16x32_bf16 v[136:139], v[128:131], v[192:195], v[136:139]
	v_mfma_f32_16x16x32_bf16 v[132:135], v[152:155], v[192:195], v[132:135]
	s_waitcnt lgkmcnt(3)
	v_mfma_f32_16x16x32_bf16 v[116:119], v[128:131], v[200:203], v[116:119]
	v_mfma_f32_16x16x32_bf16 v[112:115], v[152:155], v[200:203], v[112:115]
	s_waitcnt lgkmcnt(1)
	v_mfma_f32_16x16x32_bf16 v[76:79], v[128:131], v[224:227], v[76:79]
	v_mfma_f32_16x16x32_bf16 v[72:75], v[152:155], v[224:227], v[72:75]
	v_mfma_f32_16x16x32_bf16 v[164:167], v[140:143], v[188:191], v[164:167]
	v_mfma_f32_16x16x32_bf16 v[160:163], v[156:159], v[188:191], v[160:163]
	v_mfma_f32_16x16x32_bf16 v[136:139], v[140:143], v[196:199], v[136:139]
	v_mfma_f32_16x16x32_bf16 v[132:135], v[156:159], v[196:199], v[132:135]
	v_mfma_f32_16x16x32_bf16 v[116:119], v[140:143], v[204:207], v[116:119]
	v_mfma_f32_16x16x32_bf16 v[112:115], v[156:159], v[204:207], v[112:115]
	s_waitcnt lgkmcnt(0)
	v_mfma_f32_16x16x32_bf16 v[76:79], v[140:143], v[228:231], v[76:79]
	v_mfma_f32_16x16x32_bf16 v[72:75], v[156:159], v[228:231], v[72:75]
	v_mfma_f32_16x16x32_bf16 v[148:151], v[168:171], v[184:187], v[148:151]
	v_mfma_f32_16x16x32_bf16 v[144:147], v[176:179], v[184:187], v[144:147]
	v_mfma_f32_16x16x32_bf16 v[124:127], v[168:171], v[192:195], v[124:127]
	v_mfma_f32_16x16x32_bf16 v[120:123], v[176:179], v[192:195], v[120:123]
	v_mfma_f32_16x16x32_bf16 v[108:111], v[168:171], v[200:203], v[108:111]
	v_mfma_f32_16x16x32_bf16 v[104:107], v[176:179], v[200:203], v[104:107]
	v_mfma_f32_16x16x32_bf16 v[68:71], v[168:171], v[224:227], v[68:71]
	v_mfma_f32_16x16x32_bf16 v[64:67], v[176:179], v[224:227], v[64:67]
	v_mfma_f32_16x16x32_bf16 v[148:151], v[172:175], v[188:191], v[148:151]
	v_mfma_f32_16x16x32_bf16 v[144:147], v[180:183], v[188:191], v[144:147]
	v_mfma_f32_16x16x32_bf16 v[124:127], v[172:175], v[196:199], v[124:127]
	v_mfma_f32_16x16x32_bf16 v[120:123], v[180:183], v[196:199], v[120:123]
	v_mfma_f32_16x16x32_bf16 v[108:111], v[172:175], v[204:207], v[108:111]
	v_mfma_f32_16x16x32_bf16 v[104:107], v[180:183], v[204:207], v[104:107]
	v_mfma_f32_16x16x32_bf16 v[68:71], v[172:175], v[228:231], v[68:71]
	v_mfma_f32_16x16x32_bf16 v[64:67], v[180:183], v[228:231], v[64:67]
	s_barrier
	ds_read_b128 v[184:187], v223 offset:49152
	ds_read_b128 v[188:191], v223 offset:50176
	ds_read_b128 v[192:195], v223 offset:51200
	ds_read_b128 v[196:199], v223 offset:52224
	ds_read_b128 v[200:203], v223 offset:53248
	ds_read_b128 v[204:207], v223 offset:54272
	ds_read_b128 v[224:227], v223 offset:55296
	ds_read_b128 v[228:231], v223 offset:56320
	s_or_b32 s13, s12, 0x4000
	s_mov_b32 m0, s34
	s_nop 0
	buffer_load_dwordx4 v220, s[52:55], s13 offen lds
	s_add_i32 s12, s12, 0x164000
	s_mov_b32 m0, s82
	s_nop 0
	buffer_load_dwordx4 v221, s[52:55], s13 offen lds
	s_nop 3
	s_mov_b32 m0, s85
	s_nop 0
	buffer_load_dwordx4 v220, s[52:55], s12 offen lds
	s_nop 3
	s_mov_b32 m0, s86
	s_nop 0
	buffer_load_dwordx4 v221, s[52:55], s12 offen lds
	s_nop 3
	s_mov_b32 m0, s83
	s_nop 0
	buffer_load_dwordx4 v220, s[20:23], s11 offen lds
	s_nop 3
	s_mov_b32 m0, s84
	s_nop 0
	buffer_load_dwordx4 v221, s[20:23], s11 offen lds
	s_waitcnt vmcnt(8)
	s_waitcnt lgkmcnt(0)
	s_barrier
	s_waitcnt lgkmcnt(7)
	v_mfma_f32_16x16x32_bf16 v[60:63], v[128:131], v[184:187], v[60:63]
	v_mfma_f32_16x16x32_bf16 v[56:59], v[152:155], v[184:187], v[56:59]
	s_waitcnt lgkmcnt(5)
	v_mfma_f32_16x16x32_bf16 v[44:47], v[128:131], v[192:195], v[44:47]
	v_mfma_f32_16x16x32_bf16 v[40:43], v[152:155], v[192:195], v[40:43]
	s_waitcnt lgkmcnt(3)
	v_mfma_f32_16x16x32_bf16 v[28:31], v[128:131], v[200:203], v[28:31]
	v_mfma_f32_16x16x32_bf16 v[24:27], v[152:155], v[200:203], v[24:27]
	s_waitcnt lgkmcnt(1)
	v_mfma_f32_16x16x32_bf16 v[12:15], v[128:131], v[224:227], v[12:15]
	v_mfma_f32_16x16x32_bf16 v[8:11], v[152:155], v[224:227], v[8:11]
	v_mfma_f32_16x16x32_bf16 v[60:63], v[140:143], v[188:191], v[60:63]
	v_mfma_f32_16x16x32_bf16 v[56:59], v[156:159], v[188:191], v[56:59]
	v_mfma_f32_16x16x32_bf16 v[44:47], v[140:143], v[196:199], v[44:47]
	v_mfma_f32_16x16x32_bf16 v[40:43], v[156:159], v[196:199], v[40:43]
	v_mfma_f32_16x16x32_bf16 v[28:31], v[140:143], v[204:207], v[28:31]
	v_mfma_f32_16x16x32_bf16 v[24:27], v[156:159], v[204:207], v[24:27]
	s_waitcnt lgkmcnt(0)
	v_mfma_f32_16x16x32_bf16 v[12:15], v[140:143], v[228:231], v[12:15]
	v_mfma_f32_16x16x32_bf16 v[8:11], v[156:159], v[228:231], v[8:11]
	v_mfma_f32_16x16x32_bf16 v[52:55], v[168:171], v[184:187], v[52:55]
	v_mfma_f32_16x16x32_bf16 v[48:51], v[176:179], v[184:187], v[48:51]
	v_mfma_f32_16x16x32_bf16 v[36:39], v[168:171], v[192:195], v[36:39]
	v_mfma_f32_16x16x32_bf16 v[32:35], v[176:179], v[192:195], v[32:35]
	v_mfma_f32_16x16x32_bf16 v[20:23], v[168:171], v[200:203], v[20:23]
	v_mfma_f32_16x16x32_bf16 v[16:19], v[176:179], v[200:203], v[16:19]
	v_mfma_f32_16x16x32_bf16 v[4:7], v[168:171], v[224:227], v[4:7]
	v_mfma_f32_16x16x32_bf16 v[0:3], v[176:179], v[224:227], v[0:3]
	v_mfma_f32_16x16x32_bf16 v[52:55], v[172:175], v[188:191], v[52:55]
	v_mfma_f32_16x16x32_bf16 v[48:51], v[180:183], v[188:191], v[48:51]
	v_mfma_f32_16x16x32_bf16 v[36:39], v[172:175], v[196:199], v[36:39]
	v_mfma_f32_16x16x32_bf16 v[32:35], v[180:183], v[196:199], v[32:35]
	v_mfma_f32_16x16x32_bf16 v[20:23], v[172:175], v[204:207], v[20:23]
	v_mfma_f32_16x16x32_bf16 v[16:19], v[180:183], v[204:207], v[16:19]
	v_mfma_f32_16x16x32_bf16 v[4:7], v[172:175], v[228:231], v[4:7]
	v_mfma_f32_16x16x32_bf16 v[0:3], v[180:183], v[228:231], v[0:3]
	s_barrier
	s_add_i32 s10, s10, 2
	s_add_i32 s8, s8, 0x8000
	s_add_i32 s9, s9, 0x8000
.LBB0_885:
	v_add_u32_e32 v156, 0x10000, v222
	v_add_u32_e32 v180, 0x14000, v222
	ds_read_b128 v[128:131], v156
	ds_read_b128 v[140:143], v156 offset:1024
	ds_read_b128 v[152:155], v156 offset:2048
	ds_read_b128 v[156:159], v156 offset:3072
	ds_read_b128 v[168:171], v180
	ds_read_b128 v[172:175], v180 offset:1024
	ds_read_b128 v[176:179], v180 offset:2048
	ds_read_b128 v[180:183], v180 offset:3072
	s_add_i32 s11, s8, 0xffea4000
	s_cmpk_eq_i32 s10, 0x54
	s_cselect_b32 s13, s6, s11
	s_cselect_b32 s12, s7, s9
	s_or_b32 s11, s13, 0x4000
	ds_read_b128 v[184:187], v223
	ds_read_b128 v[188:191], v223 offset:1024
	ds_read_b128 v[192:195], v223 offset:2048
	ds_read_b128 v[196:199], v223 offset:3072
	ds_read_b128 v[200:203], v223 offset:4096
	ds_read_b128 v[204:207], v223 offset:5120
	ds_read_b128 v[224:227], v223 offset:6144
	ds_read_b128 v[228:231], v223 offset:7168
	s_mov_b32 m0, s87
	s_nop 0
	buffer_load_dwordx4 v220, s[20:23], s8 offen lds
	s_nop 3
	s_mov_b32 m0, s89
	s_nop 0
	buffer_load_dwordx4 v221, s[20:23], s8 offen lds
	s_waitcnt vmcnt(8)
	s_waitcnt lgkmcnt(0)
	s_barrier
	s_waitcnt lgkmcnt(7)
	v_mfma_f32_16x16x32_bf16 v[164:167], v[128:131], v[184:187], v[164:167]
	v_mfma_f32_16x16x32_bf16 v[160:163], v[152:155], v[184:187], v[160:163]
	s_waitcnt lgkmcnt(5)
	v_mfma_f32_16x16x32_bf16 v[136:139], v[128:131], v[192:195], v[136:139]
	v_mfma_f32_16x16x32_bf16 v[132:135], v[152:155], v[192:195], v[132:135]
	s_waitcnt lgkmcnt(3)
	v_mfma_f32_16x16x32_bf16 v[116:119], v[128:131], v[200:203], v[116:119]
	v_mfma_f32_16x16x32_bf16 v[112:115], v[152:155], v[200:203], v[112:115]
	s_waitcnt lgkmcnt(1)
	v_mfma_f32_16x16x32_bf16 v[76:79], v[128:131], v[224:227], v[76:79]
	v_mfma_f32_16x16x32_bf16 v[72:75], v[152:155], v[224:227], v[72:75]
	v_mfma_f32_16x16x32_bf16 v[164:167], v[140:143], v[188:191], v[164:167]
	v_mfma_f32_16x16x32_bf16 v[160:163], v[156:159], v[188:191], v[160:163]
	v_mfma_f32_16x16x32_bf16 v[136:139], v[140:143], v[196:199], v[136:139]
	v_mfma_f32_16x16x32_bf16 v[132:135], v[156:159], v[196:199], v[132:135]
	v_mfma_f32_16x16x32_bf16 v[116:119], v[140:143], v[204:207], v[116:119]
	v_mfma_f32_16x16x32_bf16 v[112:115], v[156:159], v[204:207], v[112:115]
	s_waitcnt lgkmcnt(0)
	v_mfma_f32_16x16x32_bf16 v[76:79], v[140:143], v[228:231], v[76:79]
	v_mfma_f32_16x16x32_bf16 v[72:75], v[156:159], v[228:231], v[72:75]
	v_mfma_f32_16x16x32_bf16 v[148:151], v[168:171], v[184:187], v[148:151]
	v_mfma_f32_16x16x32_bf16 v[144:147], v[176:179], v[184:187], v[144:147]
	v_mfma_f32_16x16x32_bf16 v[124:127], v[168:171], v[192:195], v[124:127]
	v_mfma_f32_16x16x32_bf16 v[120:123], v[176:179], v[192:195], v[120:123]
	v_mfma_f32_16x16x32_bf16 v[108:111], v[168:171], v[200:203], v[108:111]
	v_mfma_f32_16x16x32_bf16 v[104:107], v[176:179], v[200:203], v[104:107]
	v_mfma_f32_16x16x32_bf16 v[68:71], v[168:171], v[224:227], v[68:71]
	v_mfma_f32_16x16x32_bf16 v[64:67], v[176:179], v[224:227], v[64:67]
	v_mfma_f32_16x16x32_bf16 v[148:151], v[172:175], v[188:191], v[148:151]
	v_mfma_f32_16x16x32_bf16 v[144:147], v[180:183], v[188:191], v[144:147]
	v_mfma_f32_16x16x32_bf16 v[124:127], v[172:175], v[196:199], v[124:127]
	v_mfma_f32_16x16x32_bf16 v[120:123], v[180:183], v[196:199], v[120:123]
	v_mfma_f32_16x16x32_bf16 v[108:111], v[172:175], v[204:207], v[108:111]
	v_mfma_f32_16x16x32_bf16 v[104:107], v[180:183], v[204:207], v[104:107]
	v_mfma_f32_16x16x32_bf16 v[68:71], v[172:175], v[228:231], v[68:71]
	v_mfma_f32_16x16x32_bf16 v[64:67], v[180:183], v[228:231], v[64:67]
	s_barrier
	ds_read_b128 v[184:187], v223 offset:16384
	ds_read_b128 v[188:191], v223 offset:17408
	ds_read_b128 v[192:195], v223 offset:18432
	ds_read_b128 v[196:199], v223 offset:19456
	ds_read_b128 v[200:203], v223 offset:20480
	ds_read_b128 v[204:207], v223 offset:21504
	ds_read_b128 v[224:227], v223 offset:22528
	ds_read_b128 v[228:231], v223 offset:23552
	s_mov_b32 m0, s51
	s_nop 0
	buffer_load_dwordx4 v220, s[52:55], s12 offen lds
	s_add_i32 s14, s12, 0x160000
	s_mov_b32 m0, s74
	s_nop 0
	buffer_load_dwordx4 v221, s[52:55], s12 offen lds
	s_nop 3
	s_mov_b32 m0, s75
	s_nop 0
	buffer_load_dwordx4 v220, s[52:55], s14 offen lds
	s_nop 3
	s_mov_b32 m0, s76
	s_nop 0
	buffer_load_dwordx4 v221, s[52:55], s14 offen lds
	s_nop 3
	s_mov_b32 m0, s31
	s_nop 0
	buffer_load_dwordx4 v220, s[20:23], s13 offen lds
	s_nop 3
	s_mov_b32 m0, s77
	s_nop 0
	buffer_load_dwordx4 v221, s[20:23], s13 offen lds
	s_waitcnt vmcnt(8)
	s_waitcnt lgkmcnt(0)
	s_barrier
	s_waitcnt lgkmcnt(7)
	v_mfma_f32_16x16x32_bf16 v[60:63], v[128:131], v[184:187], v[60:63]
	v_mfma_f32_16x16x32_bf16 v[56:59], v[152:155], v[184:187], v[56:59]
	s_waitcnt lgkmcnt(5)
	v_mfma_f32_16x16x32_bf16 v[44:47], v[128:131], v[192:195], v[44:47]
	v_mfma_f32_16x16x32_bf16 v[40:43], v[152:155], v[192:195], v[40:43]
	s_waitcnt lgkmcnt(3)
	v_mfma_f32_16x16x32_bf16 v[28:31], v[128:131], v[200:203], v[28:31]
	v_mfma_f32_16x16x32_bf16 v[24:27], v[152:155], v[200:203], v[24:27]
	s_waitcnt lgkmcnt(1)
	v_mfma_f32_16x16x32_bf16 v[12:15], v[128:131], v[224:227], v[12:15]
	v_mfma_f32_16x16x32_bf16 v[8:11], v[152:155], v[224:227], v[8:11]
	v_mfma_f32_16x16x32_bf16 v[60:63], v[140:143], v[188:191], v[60:63]
	v_mfma_f32_16x16x32_bf16 v[56:59], v[156:159], v[188:191], v[56:59]
	v_mfma_f32_16x16x32_bf16 v[44:47], v[140:143], v[196:199], v[44:47]
	v_mfma_f32_16x16x32_bf16 v[40:43], v[156:159], v[196:199], v[40:43]
	v_mfma_f32_16x16x32_bf16 v[28:31], v[140:143], v[204:207], v[28:31]
	v_mfma_f32_16x16x32_bf16 v[24:27], v[156:159], v[204:207], v[24:27]
	s_waitcnt lgkmcnt(0)
	v_mfma_f32_16x16x32_bf16 v[12:15], v[140:143], v[228:231], v[12:15]
	v_mfma_f32_16x16x32_bf16 v[8:11], v[156:159], v[228:231], v[8:11]
	v_mfma_f32_16x16x32_bf16 v[52:55], v[168:171], v[184:187], v[52:55]
	v_mfma_f32_16x16x32_bf16 v[48:51], v[176:179], v[184:187], v[48:51]
	v_mfma_f32_16x16x32_bf16 v[36:39], v[168:171], v[192:195], v[36:39]
	v_mfma_f32_16x16x32_bf16 v[32:35], v[176:179], v[192:195], v[32:35]
	v_mfma_f32_16x16x32_bf16 v[20:23], v[168:171], v[200:203], v[20:23]
	v_mfma_f32_16x16x32_bf16 v[16:19], v[176:179], v[200:203], v[16:19]
	v_mfma_f32_16x16x32_bf16 v[4:7], v[168:171], v[224:227], v[4:7]
	v_mfma_f32_16x16x32_bf16 v[0:3], v[176:179], v[224:227], v[0:3]
	v_mfma_f32_16x16x32_bf16 v[52:55], v[172:175], v[188:191], v[52:55]
	v_mfma_f32_16x16x32_bf16 v[48:51], v[180:183], v[188:191], v[48:51]
	v_mfma_f32_16x16x32_bf16 v[36:39], v[172:175], v[196:199], v[36:39]
	v_mfma_f32_16x16x32_bf16 v[32:35], v[180:183], v[196:199], v[32:35]
	v_mfma_f32_16x16x32_bf16 v[20:23], v[172:175], v[204:207], v[20:23]
	v_mfma_f32_16x16x32_bf16 v[16:19], v[180:183], v[204:207], v[16:19]
	v_mfma_f32_16x16x32_bf16 v[4:7], v[172:175], v[228:231], v[4:7]
	v_mfma_f32_16x16x32_bf16 v[0:3], v[180:183], v[228:231], v[0:3]
	s_barrier
	v_add_u32_e32 v156, 0x18000, v222
	v_add_u32_e32 v180, 0x1c000, v222
	ds_read_b128 v[128:131], v156
	ds_read_b128 v[140:143], v156 offset:1024
	ds_read_b128 v[152:155], v156 offset:2048
	ds_read_b128 v[156:159], v156 offset:3072
	ds_read_b128 v[168:171], v180
	ds_read_b128 v[172:175], v180 offset:1024
	ds_read_b128 v[176:179], v180 offset:2048
	ds_read_b128 v[180:183], v180 offset:3072
	ds_read_b128 v[184:187], v223 offset:32768
	ds_read_b128 v[188:191], v223 offset:33792
	ds_read_b128 v[192:195], v223 offset:34816
	ds_read_b128 v[196:199], v223 offset:35840
	ds_read_b128 v[200:203], v223 offset:36864
	ds_read_b128 v[204:207], v223 offset:37888
	ds_read_b128 v[224:227], v223 offset:38912
	ds_read_b128 v[228:231], v223 offset:39936
	s_add_i32 s13, s13, 0x160000
	s_mov_b32 m0, s78
	s_nop 0
	buffer_load_dwordx4 v220, s[20:23], s13 offen lds
	s_nop 3
	s_mov_b32 m0, s79
	s_nop 0
	buffer_load_dwordx4 v221, s[20:23], s13 offen lds
	s_waitcnt vmcnt(8)
	s_waitcnt lgkmcnt(0)
	s_barrier
	s_waitcnt lgkmcnt(7)
	v_mfma_f32_16x16x32_bf16 v[164:167], v[128:131], v[184:187], v[164:167]
	v_mfma_f32_16x16x32_bf16 v[160:163], v[152:155], v[184:187], v[160:163]
	s_waitcnt lgkmcnt(5)
	v_mfma_f32_16x16x32_bf16 v[136:139], v[128:131], v[192:195], v[136:139]
	v_mfma_f32_16x16x32_bf16 v[132:135], v[152:155], v[192:195], v[132:135]
	s_waitcnt lgkmcnt(3)
	v_mfma_f32_16x16x32_bf16 v[116:119], v[128:131], v[200:203], v[116:119]
	v_mfma_f32_16x16x32_bf16 v[112:115], v[152:155], v[200:203], v[112:115]
	s_waitcnt lgkmcnt(1)
	v_mfma_f32_16x16x32_bf16 v[76:79], v[128:131], v[224:227], v[76:79]
	v_mfma_f32_16x16x32_bf16 v[72:75], v[152:155], v[224:227], v[72:75]
	v_mfma_f32_16x16x32_bf16 v[164:167], v[140:143], v[188:191], v[164:167]
	v_mfma_f32_16x16x32_bf16 v[160:163], v[156:159], v[188:191], v[160:163]
	v_mfma_f32_16x16x32_bf16 v[136:139], v[140:143], v[196:199], v[136:139]
	v_mfma_f32_16x16x32_bf16 v[132:135], v[156:159], v[196:199], v[132:135]
	v_mfma_f32_16x16x32_bf16 v[116:119], v[140:143], v[204:207], v[116:119]
	v_mfma_f32_16x16x32_bf16 v[112:115], v[156:159], v[204:207], v[112:115]
	s_waitcnt lgkmcnt(0)
	v_mfma_f32_16x16x32_bf16 v[76:79], v[140:143], v[228:231], v[76:79]
	v_mfma_f32_16x16x32_bf16 v[72:75], v[156:159], v[228:231], v[72:75]
	v_mfma_f32_16x16x32_bf16 v[148:151], v[168:171], v[184:187], v[148:151]
	v_mfma_f32_16x16x32_bf16 v[144:147], v[176:179], v[184:187], v[144:147]
	v_mfma_f32_16x16x32_bf16 v[124:127], v[168:171], v[192:195], v[124:127]
	v_mfma_f32_16x16x32_bf16 v[120:123], v[176:179], v[192:195], v[120:123]
	v_mfma_f32_16x16x32_bf16 v[108:111], v[168:171], v[200:203], v[108:111]
	v_mfma_f32_16x16x32_bf16 v[104:107], v[176:179], v[200:203], v[104:107]
	v_mfma_f32_16x16x32_bf16 v[68:71], v[168:171], v[224:227], v[68:71]
	v_mfma_f32_16x16x32_bf16 v[64:67], v[176:179], v[224:227], v[64:67]
	v_mfma_f32_16x16x32_bf16 v[148:151], v[172:175], v[188:191], v[148:151]
	v_mfma_f32_16x16x32_bf16 v[144:147], v[180:183], v[188:191], v[144:147]
	v_mfma_f32_16x16x32_bf16 v[124:127], v[172:175], v[196:199], v[124:127]
	v_mfma_f32_16x16x32_bf16 v[120:123], v[180:183], v[196:199], v[120:123]
	v_mfma_f32_16x16x32_bf16 v[108:111], v[172:175], v[204:207], v[108:111]
	v_mfma_f32_16x16x32_bf16 v[104:107], v[180:183], v[204:207], v[104:107]
	v_mfma_f32_16x16x32_bf16 v[68:71], v[172:175], v[228:231], v[68:71]
	v_mfma_f32_16x16x32_bf16 v[64:67], v[180:183], v[228:231], v[64:67]
	s_barrier
	ds_read_b128 v[184:187], v223 offset:49152
	ds_read_b128 v[188:191], v223 offset:50176
	ds_read_b128 v[192:195], v223 offset:51200
	ds_read_b128 v[196:199], v223 offset:52224
	ds_read_b128 v[200:203], v223 offset:53248
	ds_read_b128 v[204:207], v223 offset:54272
	ds_read_b128 v[224:227], v223 offset:55296
	ds_read_b128 v[228:231], v223 offset:56320
	s_or_b32 s13, s12, 0x4000
	s_mov_b32 m0, s34
	s_nop 0
	buffer_load_dwordx4 v220, s[52:55], s13 offen lds
	s_add_i32 s12, s12, 0x164000
	s_mov_b32 m0, s82
	s_nop 0
	buffer_load_dwordx4 v221, s[52:55], s13 offen lds
	s_nop 3
	s_mov_b32 m0, s85
	s_nop 0
	buffer_load_dwordx4 v220, s[52:55], s12 offen lds
	s_nop 3
	s_mov_b32 m0, s86
	s_nop 0
	buffer_load_dwordx4 v221, s[52:55], s12 offen lds
	s_nop 3
	s_mov_b32 m0, s83
	s_nop 0
	buffer_load_dwordx4 v220, s[20:23], s11 offen lds
	s_nop 3
	s_mov_b32 m0, s84
	s_nop 0
	buffer_load_dwordx4 v221, s[20:23], s11 offen lds
	s_waitcnt vmcnt(8)
	s_waitcnt lgkmcnt(0)
	s_barrier
	s_waitcnt lgkmcnt(7)
	v_mfma_f32_16x16x32_bf16 v[60:63], v[128:131], v[184:187], v[60:63]
	v_mfma_f32_16x16x32_bf16 v[56:59], v[152:155], v[184:187], v[56:59]
	s_waitcnt lgkmcnt(5)
	v_mfma_f32_16x16x32_bf16 v[44:47], v[128:131], v[192:195], v[44:47]
	v_mfma_f32_16x16x32_bf16 v[40:43], v[152:155], v[192:195], v[40:43]
	s_waitcnt lgkmcnt(3)
	v_mfma_f32_16x16x32_bf16 v[28:31], v[128:131], v[200:203], v[28:31]
	v_mfma_f32_16x16x32_bf16 v[24:27], v[152:155], v[200:203], v[24:27]
	s_waitcnt lgkmcnt(1)
	v_mfma_f32_16x16x32_bf16 v[12:15], v[128:131], v[224:227], v[12:15]
	v_mfma_f32_16x16x32_bf16 v[8:11], v[152:155], v[224:227], v[8:11]
	v_mfma_f32_16x16x32_bf16 v[60:63], v[140:143], v[188:191], v[60:63]
	v_mfma_f32_16x16x32_bf16 v[56:59], v[156:159], v[188:191], v[56:59]
	v_mfma_f32_16x16x32_bf16 v[44:47], v[140:143], v[196:199], v[44:47]
	v_mfma_f32_16x16x32_bf16 v[40:43], v[156:159], v[196:199], v[40:43]
	v_mfma_f32_16x16x32_bf16 v[28:31], v[140:143], v[204:207], v[28:31]
	v_mfma_f32_16x16x32_bf16 v[24:27], v[156:159], v[204:207], v[24:27]
	s_waitcnt lgkmcnt(0)
	v_mfma_f32_16x16x32_bf16 v[12:15], v[140:143], v[228:231], v[12:15]
	v_mfma_f32_16x16x32_bf16 v[8:11], v[156:159], v[228:231], v[8:11]
	v_mfma_f32_16x16x32_bf16 v[52:55], v[168:171], v[184:187], v[52:55]
	v_mfma_f32_16x16x32_bf16 v[48:51], v[176:179], v[184:187], v[48:51]
	v_mfma_f32_16x16x32_bf16 v[36:39], v[168:171], v[192:195], v[36:39]
	v_mfma_f32_16x16x32_bf16 v[32:35], v[176:179], v[192:195], v[32:35]
	v_mfma_f32_16x16x32_bf16 v[20:23], v[168:171], v[200:203], v[20:23]
	v_mfma_f32_16x16x32_bf16 v[16:19], v[176:179], v[200:203], v[16:19]
	v_mfma_f32_16x16x32_bf16 v[4:7], v[168:171], v[224:227], v[4:7]
	v_mfma_f32_16x16x32_bf16 v[0:3], v[176:179], v[224:227], v[0:3]
	v_mfma_f32_16x16x32_bf16 v[52:55], v[172:175], v[188:191], v[52:55]
	v_mfma_f32_16x16x32_bf16 v[48:51], v[180:183], v[188:191], v[48:51]
	v_mfma_f32_16x16x32_bf16 v[36:39], v[172:175], v[196:199], v[36:39]
	v_mfma_f32_16x16x32_bf16 v[32:35], v[180:183], v[196:199], v[32:35]
	v_mfma_f32_16x16x32_bf16 v[20:23], v[172:175], v[204:207], v[20:23]
	v_mfma_f32_16x16x32_bf16 v[16:19], v[180:183], v[204:207], v[16:19]
	v_mfma_f32_16x16x32_bf16 v[4:7], v[172:175], v[228:231], v[4:7]
	v_mfma_f32_16x16x32_bf16 v[0:3], v[180:183], v[228:231], v[0:3]
	s_barrier
	s_add_i32 s10, s10, 2
	s_add_i32 s8, s8, 0x8000
	s_add_i32 s9, s9, 0x8000
	s_cmpk_gt_u32 s10, 0x55
	s_cbranch_scc0 .LBB0_885
